# static priority raise for waves 4-7 during GEMM phases, per-phase s_setprio flips removed
# speedup vs baseline: 1.0034x; 1.0028x over previous
; #define LAS __attribute__((address_space(3)))
; __device__ __forceinline__ int opaque_tid() { int t = threadIdx.x; asm volatile("" : "+v"(t)); return t; }
;     __device__ bool next(int i, Unit& u) const {
;         const long L = (long)i * G + c; if (L >= nwg) return false;
;         int wgid = (int)L; { const int q = nwg / NXCD, r = nwg % NXCD, xcd = wgid % NXCD, off = wgid / NXCD; wgid = (xcd < r ? xcd * (q + 1) : r * (q + 1) + (xcd - r) * q) + off; }
;         const int nig = wgm * nN, gid = wgid / nig, fm = gid * wgm, gsz = (nM - fm) < wgm ? (nM - fm) : wgm;
;         u.pm = fm + ((wgid % nig) % gsz); u.pn = (wgid % nig) / gsz; return true;
;     }
; template <class Epi>
; __device__ __forceinline__ void gemm_phase(LAS unsigned char* lds, const Gemm g, const StaticOrder& S, const Epi& E) {
;     const int tid = opaque_tid(), wid = __builtin_amdgcn_readfirstlane(tid >> 6), lane = tid & 63, wr = wid >> 2, wc = wid & 3, fr = lane & 15, fq = lane >> 4;
.LBB0_125:
	s_cmp_gt_i32 s27, 4
	s_mov_b64 s[0:1], -1
	s_cbranch_scc0 .LBB0_147
	s_waitcnt vmcnt(0)
	v_mov_b32_e32 v0, v220
	v_readlane_b32 s0, v253, 19
	s_cmpk_gt_i32 s0, 0x7ff
	v_readfirstlane_b32 s31, v0
	s_cbranch_scc1 .LBB0_146
	s_cmpk_gt_u32 s31, 0xff
	s_cbranch_scc0 .Lprio_skip_s31
	s_setprio 1
.Lprio_skip_s31:
	v_readlane_b32 s1, v253, 19
	s_ashr_i32 s33, s1, 31
	s_lshr_b32 s0, s33, 29
	s_add_i32 s14, s1, s0
	s_and_b32 s0, s14, -8
	s_sub_i32 s4, s1, s0
	s_cmp_gt_i32 s4, -1
	s_mov_b64 s[0:1], -1
	s_cbranch_scc0 .LBB0_129
	s_lshl_b32 s5, s4, 8
	s_mov_b64 s[0:1], 0

; __device__ __forceinline__ unsigned cvt_pk_bf16(float lo, float hi) { unsigned r; asm volatile("v_cvt_pk_bf16_f32 %0, %1, %2" : "=v"(r) : "v"(lo), "v"(hi)); return r; }
;     __device__ __forceinline__ void operator()(const f32x4 (&acc)[2][2][4][2], const Unit& u, int wr, int wc, int fr, int fq) const {
;         const int row0 = u.pm * BM + wr * 64 + fr, col0 = u.pn * BM + wc * 32 + 8 * fq;
; #pragma unroll
;         for (int ai = 0; ai < 2; ++ai)
; #pragma unroll
;             for (int m = 0; m < 4; ++m) {
;                 const int rowi = row0 + ai * HALF + m * 16;
; #pragma unroll
;                 for (int bj = 0; bj < 2; ++bj) {
;                     f32x4 v0 = acc[ai][bj][m][0], v1 = acc[ai][bj][m][1];
; #pragma unroll
;                     for (int j = 0; j < 4; ++j) { const float a = fmaxf(v0[j], 0.f), b = fmaxf(v1[j], 0.f); v0[j] = a * a; v1[j] = b * b; }
;                     u32x4 w; w.x = cvt_pk_bf16(v0[0], v0[1]); w.y = cvt_pk_bf16(v0[2], v0[3]); w.z = cvt_pk_bf16(v1[0], v1[1]); w.w = cvt_pk_bf16(v1[2], v1[3]);
;                     *(u32x4*)(O + tiled_off(rowi, col0 + bj * HALF, DFF / 64)) = w;
;                 }
.Lpeel_done_141:
	s_lshl_b32 s24, s20, 8
	s_lshl_b32 s5, s21, 8
	s_add_i32 s24, s24, s41
	s_or_b32 s5, s5, s42
	s_and_b32 s22, s24, 0xffffff80
	s_ashr_i32 s5, s5, 6
	s_add_i32 s20, s22, s5
	s_ashr_i32 s21, s20, 31
	v_max_f32_e32 v120, 0, v120
	s_lshl_b64 s[20:21], s[20:21], 14
	v_readlane_b32 s26, v252, 57
	v_or_b32_e32 v136, s24, v132
	v_mul_f32_e32 v140, v120, v120
	v_max_f32_e32 v121, 0, v121
	v_max_f32_e32 v122, 0, v122
	v_readlane_b32 s27, v252, 58
	s_add_u32 s20, s26, s20
	v_lshlrev_b32_e32 v137, 6, v136
	s_movk_i32 s28, 0x3c0
	v_lshlrev_b32_e32 v138, 2, v136
	v_max_f32_e32 v120, 0, v125
	v_mul_f32_e32 v125, v121, v121
	v_max_f32_e32 v121, v126, v126
	v_mul_f32_e32 v126, v122, v122
	s_addc_u32 s21, s27, s21
	s_or_b32 s15, s5, 2
	v_and_or_b32 v137, v137, s28, v133
	v_and_b32_e32 v138, 32, v138
	v_max_f32_e32 v124, 0, v124
	v_mul_f32_e32 v120, v120, v120
	v_max_f32_e32 v121, 0, v121
	v_max_f32_e32 v122, 0, v127
	v_max_f32_e32 v123, 0, v123
	s_add_i32 s22, s15, s22
	v_bitop3_b32 v139, v137, s46, v138 bitop3:0xde
	v_mul_f32_e32 v124, v124, v124
	v_mul_f32_e32 v121, v121, v121
	v_mul_f32_e32 v122, v122, v122
	v_mul_f32_e32 v123, v123, v123
	v_cvt_pk_bf16_f32 v120, v124, v120
	v_max_f32_e32 v112, 0, v112
	v_max_f32_e32 v113, 0, v113
	s_ashr_i32 s23, s22, 31
	v_cvt_pk_bf16_f32 v121, v121, v122
	v_cvt_pk_bf16_f32 v122, v140, v125
	v_cvt_pk_bf16_f32 v123, v126, v123
	global_store_dwordx4 v139, v[120:123], s[20:21] nt
	v_max_f32_e32 v114, 0, v114
	s_lshl_b64 s[22:23], s[22:23], 14
	v_mul_f32_e32 v120, v112, v112
	v_max_f32_e32 v112, v117, v117
	v_mul_f32_e32 v117, v113, v113
	v_max_f32_e32 v112, 0, v112
	v_max_f32_e32 v113, 0, v118
	v_mul_f32_e32 v118, v114, v114
	s_add_u32 s22, s26, s22
	v_max_f32_e32 v116, 0, v116
	v_mul_f32_e32 v112, v112, v112
	v_mul_f32_e32 v113, v113, v113
	v_max_f32_e32 v114, 0, v119
	v_max_f32_e32 v115, 0, v115
	s_addc_u32 s23, s27, s23
	s_or_b32 s25, s24, 16
	v_mul_f32_e32 v116, v116, v116
	v_mul_f32_e32 v114, v114, v114
	v_mul_f32_e32 v115, v115, v115
	v_cvt_pk_bf16_f32 v112, v116, v112
	v_cvt_pk_bf16_f32 v113, v113, v114
	s_lshr_b32 s25, s25, 3
	v_max_f32_e32 v104, 0, v104
	v_cvt_pk_bf16_f32 v114, v120, v117
	v_cvt_pk_bf16_f32 v115, v118, v115
	global_store_dwordx4 v139, v[112:115], s[22:23] nt
	s_and_b32 s25, s25, 10
	v_max_f32_e32 v105, 0, v105
	v_mul_f32_e32 v113, v104, v104
	v_max_f32_e32 v106, 0, v106
	s_or_b32 s25, s25, s45
	v_max_f32_e32 v104, 0, v109
	v_mul_f32_e32 v109, v105, v105
	v_max_f32_e32 v105, v110, v110
	v_mul_f32_e32 v110, v106, v106
	s_lshl_b32 s25, s25, 10
	v_max_f32_e32 v108, 0, v108
	v_mul_f32_e32 v104, v104, v104
	v_max_f32_e32 v105, 0, v105
	v_max_f32_e32 v106, 0, v111
	v_max_f32_e32 v107, 0, v107
	v_bitop3_b32 v112, v137, s25, v138 bitop3:0xde
	v_mul_f32_e32 v108, v108, v108
	v_mul_f32_e32 v105, v105, v105
	v_mul_f32_e32 v106, v106, v106
	v_mul_f32_e32 v107, v107, v107
	v_cvt_pk_bf16_f32 v104, v108, v104
	v_max_f32_e32 v96, 0, v96
	v_max_f32_e32 v97, 0, v97
	v_cvt_pk_bf16_f32 v105, v105, v106
	v_cvt_pk_bf16_f32 v106, v113, v109
	v_cvt_pk_bf16_f32 v107, v110, v107
	global_store_dwordx4 v112, v[104:107], s[20:21] nt
	s_nop 0
	v_max_f32_e32 v98, 0, v98
	v_mul_f32_e32 v104, v96, v96
	v_max_f32_e32 v96, v101, v101
	v_mul_f32_e32 v101, v97, v97
	v_max_f32_e32 v96, 0, v96
	v_max_f32_e32 v97, 0, v102
	v_mul_f32_e32 v102, v98, v98
	v_max_f32_e32 v100, 0, v100
	v_mul_f32_e32 v96, v96, v96
	v_mul_f32_e32 v97, v97, v97
	v_max_f32_e32 v98, 0, v103
	v_max_f32_e32 v99, 0, v99
	s_or_b32 s25, s24, 32
	v_mul_f32_e32 v100, v100, v100
	v_mul_f32_e32 v98, v98, v98
	v_mul_f32_e32 v99, v99, v99
	v_cvt_pk_bf16_f32 v96, v100, v96
	v_cvt_pk_bf16_f32 v97, v97, v98
	s_lshr_b32 s25, s25, 3
	v_max_f32_e32 v88, 0, v88
	v_cvt_pk_bf16_f32 v98, v104, v101
	v_cvt_pk_bf16_f32 v99, v102, v99
	global_store_dwordx4 v112, v[96:99], s[22:23] nt
	s_and_b32 s25, s25, 12
	v_max_f32_e32 v89, 0, v89
	v_mul_f32_e32 v97, v88, v88
	v_max_f32_e32 v90, 0, v90
	s_or_b32 s25, s25, s45
	v_max_f32_e32 v88, 0, v93
	v_mul_f32_e32 v93, v89, v89
	v_max_f32_e32 v89, v94, v94
	v_mul_f32_e32 v94, v90, v90
	s_lshl_b32 s25, s25, 10
	v_max_f32_e32 v92, 0, v92
	v_mul_f32_e32 v88, v88, v88
	v_max_f32_e32 v89, 0, v89
	v_max_f32_e32 v90, 0, v95
	v_max_f32_e32 v91, 0, v91
	v_bitop3_b32 v96, v137, s25, v138 bitop3:0xde
	v_mul_f32_e32 v92, v92, v92
	v_mul_f32_e32 v89, v89, v89
	v_mul_f32_e32 v90, v90, v90
	v_mul_f32_e32 v91, v91, v91
	v_cvt_pk_bf16_f32 v88, v92, v88
	v_max_f32_e32 v80, 0, v80
	v_max_f32_e32 v81, 0, v81
	v_cvt_pk_bf16_f32 v89, v89, v90
	v_cvt_pk_bf16_f32 v90, v97, v93
	v_cvt_pk_bf16_f32 v91, v94, v91
	global_store_dwordx4 v96, v[88:91], s[20:21] nt
	s_nop 0
	v_max_f32_e32 v82, 0, v82
	v_mul_f32_e32 v88, v80, v80
	v_max_f32_e32 v80, v85, v85
	v_mul_f32_e32 v85, v81, v81
	v_max_f32_e32 v80, 0, v80
	v_max_f32_e32 v81, 0, v86
	v_mul_f32_e32 v86, v82, v82
	v_max_f32_e32 v84, 0, v84
	v_mul_f32_e32 v80, v80, v80
	v_mul_f32_e32 v81, v81, v81
	v_max_f32_e32 v82, 0, v87
	v_max_f32_e32 v83, 0, v83
	s_or_b32 s24, s24, 48
	v_mul_f32_e32 v84, v84, v84
	v_mul_f32_e32 v82, v82, v82
	v_mul_f32_e32 v83, v83, v83
	v_cvt_pk_bf16_f32 v80, v84, v80
	v_cvt_pk_bf16_f32 v81, v81, v82
	s_lshr_b32 s24, s24, 3
	v_max_f32_e32 v72, 0, v72
	v_cvt_pk_bf16_f32 v82, v88, v85
	v_cvt_pk_bf16_f32 v83, v86, v83
	global_store_dwordx4 v96, v[80:83], s[22:23] nt
	s_and_b32 s24, s24, 14
	v_max_f32_e32 v73, 0, v73
	v_mul_f32_e32 v81, v72, v72
	v_max_f32_e32 v74, 0, v74
	s_or_b32 s24, s24, s45
	v_max_f32_e32 v72, 0, v77
	v_mul_f32_e32 v77, v73, v73
	v_max_f32_e32 v73, v78, v78
	v_mul_f32_e32 v78, v74, v74
	s_lshl_b32 s24, s24, 10
	v_max_f32_e32 v76, 0, v76
	v_mul_f32_e32 v72, v72, v72
; __device__ __forceinline__ unsigned cvt_pk_bf16(float lo, float hi) { unsigned r; asm volatile("v_cvt_pk_bf16_f32 %0, %1, %2" : "=v"(r) : "v"(lo), "v"(hi)); return r; }
;     __device__ __forceinline__ void operator()(const f32x4 (&acc)[2][2][4][2], const Unit& u, int wr, int wc, int fr, int fq) const {
;         const int row0 = u.pm * BM + wr * 64 + fr, col0 = u.pn * BM + wc * 32 + 8 * fq;
; #pragma unroll
;         for (int ai = 0; ai < 2; ++ai)
; #pragma unroll
;             for (int m = 0; m < 4; ++m) {
;                 const int rowi = row0 + ai * HALF + m * 16;
; #pragma unroll
;                 for (int bj = 0; bj < 2; ++bj) {
;                     f32x4 v0 = acc[ai][bj][m][0], v1 = acc[ai][bj][m][1];
; #pragma unroll
;                     for (int j = 0; j < 4; ++j) { const float a = fmaxf(v0[j], 0.f), b = fmaxf(v1[j], 0.f); v0[j] = a * a; v1[j] = b * b; }
;                     u32x4 w; w.x = cvt_pk_bf16(v0[0], v0[1]); w.y = cvt_pk_bf16(v0[2], v0[3]); w.z = cvt_pk_bf16(v1[0], v1[1]); w.w = cvt_pk_bf16(v1[2], v1[3]);
;                     *(u32x4*)(O + tiled_off(rowi, col0 + bj * HALF, DFF / 64)) = w;
;                 }
	v_max_f32_e32 v73, 0, v73
	v_max_f32_e32 v74, 0, v79
	v_max_f32_e32 v75, 0, v75
	v_bitop3_b32 v80, v137, s24, v138 bitop3:0xde
	v_mul_f32_e32 v76, v76, v76
	v_mul_f32_e32 v73, v73, v73
	v_mul_f32_e32 v74, v74, v74
	v_mul_f32_e32 v75, v75, v75
	v_cvt_pk_bf16_f32 v72, v76, v72
	v_max_f32_e32 v64, 0, v64
	v_cvt_pk_bf16_f32 v73, v73, v74
	v_cvt_pk_bf16_f32 v74, v81, v77
	v_cvt_pk_bf16_f32 v75, v78, v75
	global_store_dwordx4 v80, v[72:75], s[20:21] nt
	v_max_f32_e32 v65, 0, v65
	v_max_f32_e32 v66, 0, v66
	v_mul_f32_e32 v72, v64, v64
	v_max_f32_e32 v64, 0, v69
	v_mul_f32_e32 v69, v65, v65
	v_max_f32_e32 v65, v70, v70
	v_mul_f32_e32 v70, v66, v66
	v_max_f32_e32 v68, 0, v68
	v_mul_f32_e32 v64, v64, v64
	v_max_f32_e32 v65, 0, v65
	v_max_f32_e32 v66, 0, v71
	v_max_f32_e32 v67, 0, v67
	v_mul_f32_e32 v68, v68, v68
	v_mul_f32_e32 v65, v65, v65
	v_mul_f32_e32 v66, v66, v66
	v_mul_f32_e32 v67, v67, v67
	v_cvt_pk_bf16_f32 v64, v68, v64
	v_cvt_pk_bf16_f32 v65, v65, v66
	v_cvt_pk_bf16_f32 v66, v72, v69
	v_cvt_pk_bf16_f32 v67, v70, v67
	global_store_dwordx4 v80, v[64:67], s[22:23] nt
	s_nop 0
	v_max_f32_e32 v56, 0, v56
	v_add_u32_e32 v64, 0x80, v136
	v_and_b32_e32 v65, 0xffffff80, v64
	v_lshlrev_b32_e32 v66, 6, v64
	v_lshlrev_b32_e32 v64, 2, v64
	v_and_or_b32 v66, v66, s28, v133
	v_and_b32_e32 v64, 32, v64
	v_bitop3_b32 v152, v66, s46, v64 bitop3:0xde
	v_mul_f32_e32 v64, v56, v56
	v_max_f32_e32 v57, 0, v57
	v_max_f32_e32 v58, 0, v58
	v_max_f32_e32 v60, 0, v60
	v_max_f32_e32 v56, 0, v61
	v_mul_f32_e32 v61, v57, v57
	v_max_f32_e32 v57, v62, v62
	v_mul_f32_e32 v62, v58, v58
	v_mul_f32_e32 v60, v60, v60
	v_mul_f32_e32 v56, v56, v56
	v_max_f32_e32 v57, 0, v57
	v_max_f32_e32 v58, 0, v63
	v_mul_f32_e32 v57, v57, v57
	v_mul_f32_e32 v58, v58, v58
	v_cvt_pk_bf16_f32 v56, v60, v56
	v_add_u32_e32 v60, s5, v65
	v_cvt_pk_bf16_f32 v57, v57, v58
	v_cvt_pk_bf16_f32 v58, v64, v61
	v_ashrrev_i32_e32 v61, 31, v60
	v_max_f32_e32 v59, 0, v59
	v_lshlrev_b64 v[60:61], 14, v[60:61]
	v_mul_f32_e32 v59, v59, v59
	v_lshl_add_u64 v[60:61], s[26:27], 0, v[60:61]
	v_cvt_pk_bf16_f32 v59, v62, v59
	v_lshl_add_u64 v[62:63], v[60:61], 0, v[152:153]
	v_max_f32_e32 v48, 0, v48
	global_store_dwordx4 v[62:63], v[56:59], off nt
	s_nop 0
	v_max_f32_e32 v49, 0, v49
	v_mul_f32_e32 v56, v48, v48
	v_max_f32_e32 v50, 0, v50
	v_max_f32_e32 v52, 0, v52
	v_max_f32_e32 v48, 0, v53
	v_mul_f32_e32 v53, v49, v49
	v_max_f32_e32 v49, v54, v54
	v_mul_f32_e32 v54, v50, v50
	v_mul_f32_e32 v52, v52, v52
	v_mul_f32_e32 v48, v48, v48
	v_max_f32_e32 v49, 0, v49
	v_max_f32_e32 v50, 0, v55
	v_mul_f32_e32 v49, v49, v49
	v_mul_f32_e32 v50, v50, v50
	v_cvt_pk_bf16_f32 v48, v52, v48
	v_add_u32_e32 v52, s15, v65
	v_cvt_pk_bf16_f32 v49, v49, v50
	v_cvt_pk_bf16_f32 v50, v56, v53
	v_ashrrev_i32_e32 v53, 31, v52
	v_max_f32_e32 v51, 0, v51
	v_lshlrev_b64 v[52:53], 14, v[52:53]
	v_mul_f32_e32 v51, v51, v51
	v_lshl_add_u64 v[52:53], s[26:27], 0, v[52:53]
	v_cvt_pk_bf16_f32 v51, v54, v51
	v_lshl_add_u64 v[54:55], v[52:53], 0, v[152:153]
	global_store_dwordx4 v[54:55], v[48:51], off nt
	s_nop 1
	v_add_u32_e32 v48, 0x90, v136
	v_lshrrev_b32_e32 v49, 3, v48
	v_and_or_b32 v49, v49, 10, s45
	v_lshlrev_b32_e32 v50, 6, v48
	v_lshlrev_b32_e32 v48, 2, v48
	v_and_or_b32 v50, v50, s28, v133
	v_lshlrev_b32_e32 v49, 10, v49
	v_and_b32_e32 v48, 32, v48
	v_max_f32_e32 v40, 0, v40
	v_max_f32_e32 v41, 0, v41
	v_max_f32_e32 v42, 0, v42
	v_bitop3_b32 v152, v50, v49, v48 bitop3:0xde
	v_mul_f32_e32 v48, v40, v40
	v_max_f32_e32 v40, v45, v45
	v_mul_f32_e32 v45, v41, v41
	v_max_f32_e32 v41, v46, v46
	v_mul_f32_e32 v46, v42, v42
	v_max_f32_e32 v44, 0, v44
	v_max_f32_e32 v40, 0, v40
	v_max_f32_e32 v41, 0, v41
	v_max_f32_e32 v42, 0, v47
	v_mul_f32_e32 v44, v44, v44
	v_mul_f32_e32 v40, v40, v40
	v_mul_f32_e32 v41, v41, v41
	v_max_f32_e32 v43, 0, v43
	v_mul_f32_e32 v42, v42, v42
	v_mul_f32_e32 v43, v43, v43
	v_cvt_pk_bf16_f32 v40, v44, v40
	v_cvt_pk_bf16_f32 v41, v41, v42
	v_cvt_pk_bf16_f32 v42, v48, v45
	v_lshl_add_u64 v[44:45], v[60:61], 0, v[152:153]
	v_max_f32_e32 v32, 0, v32
	v_max_f32_e32 v33, 0, v33
	v_max_f32_e32 v34, 0, v34
	v_cvt_pk_bf16_f32 v43, v46, v43
	global_store_dwordx4 v[44:45], v[40:43], off nt
	s_nop 0
	v_max_f32_e32 v36, 0, v36
	v_mul_f32_e32 v40, v32, v32
	v_max_f32_e32 v32, v37, v37
	v_mul_f32_e32 v37, v33, v33
	v_max_f32_e32 v33, v38, v38
; __device__ __forceinline__ unsigned cvt_pk_bf16(float lo, float hi) { unsigned r; asm volatile("v_cvt_pk_bf16_f32 %0, %1, %2" : "=v"(r) : "v"(lo), "v"(hi)); return r; }
; #define PG8_WAIT_V(n) asm volatile("s_waitcnt vmcnt(" #n ")" ::: "memory")
; #define PG8_BAR __builtin_amdgcn_s_barrier()
; template <class Epi>
; __device__ __forceinline__ void gemm_phase(LAS unsigned char* lds, const Gemm g, const StaticOrder& S, const Epi& E) {
;     ...
;         E(acc, cur, wr, wc, fr, fq);
;         if (!has_next) break;
; #pragma unroll
;         for (int a = 0; a < 2; ++a)
; #pragma unroll
;             for (int b = 0; b < 2; ++b)
; #pragma unroll
;                 for (int m = 0; m < 4; ++m)
; #pragma unroll
;                     for (int n = 0; n < 2; ++n) acc[a][b][m][n] = (f32x4){0.f, 0.f, 0.f, 0.f};
;         cur = nxt; cA = nA; cB = nB; ++ui;
;     }
;     PG8_WAIT_V(0);
;     if (wr == 0) PG8_BAR;
;     PG8_BAR;
;     __device__ __forceinline__ void operator()(const f32x4 (&acc)[2][2][4][2], const Unit& u, int wr, int wc, int fr, int fq) const {
;     ...
;         for (int ai = 0; ai < 2; ++ai)
; #pragma unroll
;             for (int m = 0; m < 4; ++m) {
;                 const int rowi = row0 + ai * HALF + m * 16;
; #pragma unroll
;                 for (int bj = 0; bj < 2; ++bj) {
;                     f32x4 v0 = acc[ai][bj][m][0], v1 = acc[ai][bj][m][1];
; #pragma unroll
;                     for (int j = 0; j < 4; ++j) { const float a = fmaxf(v0[j], 0.f), b = fmaxf(v1[j], 0.f); v0[j] = a * a; v1[j] = b * b; }
;                     u32x4 w; w.x = cvt_pk_bf16(v0[0], v0[1]); w.y = cvt_pk_bf16(v0[2], v0[3]); w.z = cvt_pk_bf16(v1[0], v1[1]); w.w = cvt_pk_bf16(v1[2], v1[3]);
;                     *(u32x4*)(O + tiled_off(rowi, col0 + bj * HALF, DFF / 64)) = w;
;                 }
	v_mul_f32_e32 v38, v34, v34
	v_max_f32_e32 v32, 0, v32
	v_max_f32_e32 v33, 0, v33
	v_max_f32_e32 v34, 0, v39
	v_mul_f32_e32 v36, v36, v36
	v_mul_f32_e32 v32, v32, v32
	v_mul_f32_e32 v33, v33, v33
	v_max_f32_e32 v35, 0, v35
	v_mul_f32_e32 v34, v34, v34
	v_mul_f32_e32 v35, v35, v35
	v_cvt_pk_bf16_f32 v32, v36, v32
	v_cvt_pk_bf16_f32 v33, v33, v34
	v_cvt_pk_bf16_f32 v34, v40, v37
	v_lshl_add_u64 v[36:37], v[52:53], 0, v[152:153]
	v_cvt_pk_bf16_f32 v35, v38, v35
	global_store_dwordx4 v[36:37], v[32:35], off nt
	s_nop 1
	v_add_u32_e32 v32, 0xa0, v136
	v_lshrrev_b32_e32 v33, 3, v32
	v_and_or_b32 v33, v33, 12, s45
	v_lshlrev_b32_e32 v34, 6, v32
	v_lshlrev_b32_e32 v32, 2, v32
	v_and_or_b32 v34, v34, s28, v133
	v_lshlrev_b32_e32 v33, 10, v33
	v_and_b32_e32 v32, 32, v32
	v_max_f32_e32 v24, 0, v24
	v_max_f32_e32 v25, 0, v25
	v_max_f32_e32 v26, 0, v26
	v_bitop3_b32 v152, v34, v33, v32 bitop3:0xde
	v_mul_f32_e32 v32, v24, v24
	v_max_f32_e32 v24, v29, v29
	v_mul_f32_e32 v29, v25, v25
	v_max_f32_e32 v25, v30, v30
	v_mul_f32_e32 v30, v26, v26
	v_max_f32_e32 v28, 0, v28
	v_max_f32_e32 v24, 0, v24
	v_max_f32_e32 v25, 0, v25
	v_max_f32_e32 v26, 0, v31
	v_mul_f32_e32 v28, v28, v28
	v_mul_f32_e32 v24, v24, v24
	v_mul_f32_e32 v25, v25, v25
	v_max_f32_e32 v27, 0, v27
	v_mul_f32_e32 v26, v26, v26
	v_mul_f32_e32 v27, v27, v27
	v_cvt_pk_bf16_f32 v24, v28, v24
	v_cvt_pk_bf16_f32 v25, v25, v26
	v_cvt_pk_bf16_f32 v26, v32, v29
	v_lshl_add_u64 v[28:29], v[60:61], 0, v[152:153]
	v_max_f32_e32 v16, 0, v16
	v_max_f32_e32 v17, 0, v17
	v_max_f32_e32 v18, 0, v18
	v_cvt_pk_bf16_f32 v27, v30, v27
	global_store_dwordx4 v[28:29], v[24:27], off nt
	s_nop 0
	v_max_f32_e32 v20, 0, v20
	v_mul_f32_e32 v24, v16, v16
	v_max_f32_e32 v16, v21, v21
	v_mul_f32_e32 v21, v17, v17
	v_max_f32_e32 v17, v22, v22
	v_mul_f32_e32 v22, v18, v18
	v_max_f32_e32 v16, 0, v16
	v_max_f32_e32 v17, 0, v17
	v_max_f32_e32 v18, 0, v23
	v_mul_f32_e32 v20, v20, v20
	v_mul_f32_e32 v16, v16, v16
	v_mul_f32_e32 v17, v17, v17
	v_max_f32_e32 v19, 0, v19
	v_mul_f32_e32 v18, v18, v18
	v_mul_f32_e32 v19, v19, v19
	v_cvt_pk_bf16_f32 v16, v20, v16
	v_cvt_pk_bf16_f32 v17, v17, v18
	v_cvt_pk_bf16_f32 v18, v24, v21
	v_lshl_add_u64 v[20:21], v[52:53], 0, v[152:153]
	v_cvt_pk_bf16_f32 v19, v22, v19
	global_store_dwordx4 v[20:21], v[16:19], off nt
	s_nop 1
	v_add_u32_e32 v16, 0xb0, v136
	v_lshrrev_b32_e32 v17, 3, v16
	v_and_or_b32 v17, v17, 14, s45
	v_lshlrev_b32_e32 v18, 6, v16
	v_lshlrev_b32_e32 v16, 2, v16
	v_and_or_b32 v18, v18, s28, v133
	v_lshlrev_b32_e32 v17, 10, v17
	v_and_b32_e32 v16, 32, v16
	v_max_f32_e32 v8, 0, v8
	v_max_f32_e32 v9, 0, v9
	v_max_f32_e32 v10, 0, v10
	v_bitop3_b32 v152, v18, v17, v16 bitop3:0xde
	v_mul_f32_e32 v16, v8, v8
	v_max_f32_e32 v8, v13, v13
	v_mul_f32_e32 v13, v9, v9
	v_max_f32_e32 v9, v14, v14
	v_mul_f32_e32 v14, v10, v10
	v_max_f32_e32 v12, 0, v12
	v_max_f32_e32 v8, 0, v8
	v_max_f32_e32 v9, 0, v9
	v_max_f32_e32 v10, 0, v15
	v_mul_f32_e32 v12, v12, v12
	v_mul_f32_e32 v8, v8, v8
	v_mul_f32_e32 v9, v9, v9
	v_max_f32_e32 v11, 0, v11
	v_mul_f32_e32 v10, v10, v10
	v_mul_f32_e32 v11, v11, v11
	v_cvt_pk_bf16_f32 v8, v12, v8
	v_cvt_pk_bf16_f32 v9, v9, v10
	v_cvt_pk_bf16_f32 v10, v16, v13
	v_lshl_add_u64 v[12:13], v[60:61], 0, v[152:153]
	v_max_f32_e32 v0, 0, v0
	v_max_f32_e32 v1, 0, v1
	v_max_f32_e32 v2, 0, v2
	v_cvt_pk_bf16_f32 v11, v14, v11
	global_store_dwordx4 v[12:13], v[8:11], off nt
	s_nop 0
	v_max_f32_e32 v4, 0, v4
	v_mul_f32_e32 v8, v0, v0
	v_max_f32_e32 v0, v5, v5
	v_mul_f32_e32 v5, v1, v1
	v_max_f32_e32 v1, v6, v6
	v_mul_f32_e32 v6, v2, v2
	v_max_f32_e32 v0, 0, v0
	v_max_f32_e32 v1, 0, v1
	v_max_f32_e32 v2, 0, v7
	v_mul_f32_e32 v4, v4, v4
	v_mul_f32_e32 v0, v0, v0
	v_mul_f32_e32 v1, v1, v1
	v_max_f32_e32 v3, 0, v3
	v_mul_f32_e32 v2, v2, v2
	s_mov_b32 s54, 0xd00ab22c
	v_mul_f32_e32 v3, v3, v3
	v_cvt_pk_bf16_f32 v0, v4, v0
	v_cvt_pk_bf16_f32 v1, v1, v2
	v_cvt_pk_bf16_f32 v2, v8, v5
	v_lshl_add_u64 v[4:5], v[52:53], 0, v[152:153]
	s_and_b64 vcc, exec, s[0:1]
	s_mov_b32 s21, s4
	s_mov_b32 s20, s14
	s_mov_b64 s[24:25], s[18:19]
	s_mov_b64 s[22:23], s[16:17]
	s_mov_b32 s55, 0x3febb5fa
	v_cvt_pk_bf16_f32 v3, v6, v3
	global_store_dwordx4 v[4:5], v[0:3], off nt
	s_cbranch_vccz .LBB0_134
	s_waitcnt vmcnt(0)
	s_setprio 0
	s_cmpk_gt_u32 s31, 0xff
	s_cbranch_scc1 .LBB0_145
	s_barrier

; #define LAS __attribute__((address_space(3)))
; __device__ __forceinline__ int opaque_tid() { int t = threadIdx.x; asm volatile("" : "+v"(t)); return t; }
;     __device__ bool next(int i, Unit& u) const {
;         const long L = (long)i * G + c; if (L >= nwg) return false;
;         int wgid = (int)L; { const int q = nwg / NXCD, r = nwg % NXCD, xcd = wgid % NXCD, off = wgid / NXCD; wgid = (xcd < r ? xcd * (q + 1) : r * (q + 1) + (xcd - r) * q) + off; }
;         const int nig = wgm * nN, gid = wgid / nig, fm = gid * wgm, gsz = (nM - fm) < wgm ? (nM - fm) : wgm;
;         u.pm = fm + ((wgid % nig) % gsz); u.pn = (wgid % nig) / gsz; return true;
;     }
; template <class Epi>
; __device__ __forceinline__ void gemm_phase(LAS unsigned char* lds, const Gemm g, const StaticOrder& S, const Epi& E) {
;     const int tid = opaque_tid(), wid = __builtin_amdgcn_readfirstlane(tid >> 6), lane = tid & 63, wr = wid >> 2, wc = wid & 3, fr = lane & 15, fq = lane >> 4;
.LBB0_165:
	v_readlane_b32 s6, v253, 19
	s_waitcnt vmcnt(0)
	v_mov_b32_e32 v0, v220
	s_cmpk_lt_i32 s6, 0x200
	s_cselect_b64 s[4:5], -1, 0
	s_cmpk_gt_i32 s6, 0x1ff
	v_readfirstlane_b32 s29, v0
	s_cbranch_scc1 .LBB0_171
	s_cmpk_gt_u32 s29, 0xff
	s_cbranch_scc0 .Lprio_skip_s29
	s_setprio 1
.Lprio_skip_s29:
	v_readlane_b32 s7, v253, 19
	s_ashr_i32 s6, s7, 31
	s_lshr_b32 s6, s6, 29
	s_add_i32 s20, s7, s6
	s_and_b32 s6, s20, -8
	s_sub_i32 s21, s7, s6
	s_cmp_gt_i32 s21, -1
	s_mov_b64 s[6:7], -1
	s_cbranch_scc0 .LBB0_168
	s_lshl_b32 s22, s21, 6
	s_mov_b64 s[6:7], 0

; #define PG8_STAGE(bufoff, gbase, voff) do { _Pragma("unroll") for (int _i = 0; _i < 2; ++_i) \
;         __builtin_amdgcn_global_load_lds((const unsigned*)((const char*)(gbase) + (voff)[_i]), (LAS unsigned*)(lds + (bufoff) + ldsw + _i * 8192), 16, 0, 0); } while (0)
; #define PG8_LDA(dst, b, h) do { _Pragma("unroll") for (int m = 0; m < 4; ++m) _Pragma("unroll") for (int k = 0; k < 2; ++k) dst[m][k] = *(const LAS bf16x8*)(lds + PG8_SA(b, h) + aoff + m * 2048 + k * 1024); } while (0)
; #define PG8_LDB(dst, b, h) do { _Pragma("unroll") for (int n = 0; n < 2; ++n) _Pragma("unroll") for (int k = 0; k < 2; ++k) dst[n][k] = *(const LAS bf16x8*)(lds + PG8_SB(b, h) + boff + n * 2048 + k * 1024); } while (0)
; #define PG8_MMA(ai, bj, At, Bt) do { __builtin_amdgcn_s_setprio(1); _Pragma("unroll") for (int m = 0; m < 4; ++m) _Pragma("unroll") for (int n = 0; n < 2; ++n) _Pragma("unroll") for (int k = 0; k < 2; ++k) \
;         acc[ai][bj][m][n] = __builtin_amdgcn_mfma_f32_16x16x32_bf16(Bt[n][k], At[m][k], acc[ai][bj][m][n], 0, 0, 0); __builtin_amdgcn_s_setprio(0); } while (0)
; template <class Epi>
; __device__ __forceinline__ void gemm_phase(LAS unsigned char* lds, const Gemm g, const StaticOrder& S, const Epi& E) {
;     ...
;         const char* nA = has_next ? (const char*)g.A + (size_t)nxt.pm * tstepA : cA; const char* nB = has_next ? (const char*)g.Bt + (size_t)nxt.pn * tstepB : cB;
;         for (int t = 0; t < nt; t += 2) {
;             const bool last = (t == nt - 2);
;             const char* a1 = cA + (size_t)(t + 1) * kstep;
;             const char* a2 = last ? nA : cA + (size_t)(t + 2) * kstep; const char* b2 = last ? nB : cB + (size_t)(t + 2) * kstep;
;             const char* a3 = a2 + kstep; const char* b3 = b2 + kstep;
;             PG8_LDB(B0, 0, 0); PG8_SCHED; PG8_LDA(At, 0, 0); PG8_STAGE(PG8_SA(1, 1), a1 + hstepA, voffA);
;             PG8_WAIT_L(8); PG8_BAR; PG8_WAIT_L(0); PG8_MMA(0, 0, At, B0); PG8_BAR; PG8_SCHED;
;             PG8_LDB(B1, 0, 1); PG8_STAGE(PG8_SB(0, 0), b2, voffB);
;             PG8_BAR; PG8_WAIT_L(0); PG8_MMA(0, 1, At, B1); PG8_BAR;
;             PG8_LDA(At, 0, 1); PG8_STAGE(PG8_SA(0, 0), a2, voffA);
;             PG8_BAR; PG8_WAIT_L(0); PG8_MMA(1, 0, At, B0); PG8_BAR; PG8_SCHED;
;             PG8_STAGE(PG8_SB(0, 1), b2 + hstepB, voffB);
;             PG8_WAIT_V(6); PG8_BAR; PG8_MMA(1, 1, At, B1); PG8_BAR;
.LBB0_186:
	s_add_u32 s4, s24, 0x4000
	s_addc_u32 s5, s25, 0
	s_add_u32 s50, s22, 0x8000
	s_addc_u32 s51, s23, 0
	s_mov_b32 s22, 0
	s_add_i32 s54, s22, 2
	s_add_u32 s23, s4, 0x4000
	s_addc_u32 s24, s5, 0
	s_cmp_eq_u32 s40, s22
	s_cselect_b32 s26, s6, s23
	s_cselect_b32 s27, s7, s24
	s_cselect_b32 s24, s20, s50
	s_cselect_b32 s25, s21, s51
	s_add_u32 s22, s26, 0x4000
	s_addc_u32 s23, s27, 0
	s_add_i32 m0, s33, 0xc000
	v_lshl_add_u64 v[186:187], s[4:5], 0, v[158:159]
	global_load_lds_dwordx4 v[186:187], off nt
	s_add_i32 m0, s33, 0xe000
	v_lshl_add_u64 v[186:187], s[4:5], 0, v[160:161]
	global_load_lds_dwordx4 v[186:187], off nt
	s_mov_b32 s55, 0x10000
	v_add_u32_e32 v140, s55, v207
	ds_read_b128 v[128:131], v140
	ds_read_b128 v[136:139], v140 offset:2048
	ds_read_b128 v[132:135], v140 offset:1024
	ds_read_b128 v[140:143], v140 offset:3072
	ds_read_b128 v[144:147], v209
	ds_read_b128 v[162:165], v209 offset:2048
	ds_read_b128 v[170:173], v209 offset:4096
	ds_read_b128 v[178:181], v209 offset:6144
	ds_read_b128 v[148:151], v209 offset:1024
	ds_read_b128 v[166:169], v209 offset:3072
	ds_read_b128 v[174:177], v209 offset:5120
	ds_read_b128 v[182:185], v209 offset:7168
	s_mov_b32 s58, 0x14000
	s_add_i32 s55, s55, s31
	v_add_u32_e32 v198, s58, v207
	ds_read_b128 v[186:189], v198
	ds_read_b128 v[194:197], v198 offset:2048
	ds_read_b128 v[190:193], v198 offset:1024
	ds_read_b128 v[198:201], v198 offset:3072
	s_waitcnt lgkmcnt(0)
	s_barrier
	v_mfma_f32_16x16x32_bf16 v[124:127], v[128:131], v[144:147], 0
	v_mfma_f32_16x16x32_bf16 v[120:123], v[136:139], v[144:147], 0
	v_mfma_f32_16x16x32_bf16 v[116:119], v[128:131], v[162:165], 0
	v_mfma_f32_16x16x32_bf16 v[112:115], v[136:139], v[162:165], 0
	v_mfma_f32_16x16x32_bf16 v[108:111], v[128:131], v[170:173], 0
	v_mfma_f32_16x16x32_bf16 v[104:107], v[136:139], v[170:173], 0
	v_mfma_f32_16x16x32_bf16 v[100:103], v[128:131], v[178:181], 0
	v_mfma_f32_16x16x32_bf16 v[96:99], v[136:139], v[178:181], 0
	v_mfma_f32_16x16x32_bf16 v[124:127], v[132:135], v[148:151], v[124:127]
	v_mfma_f32_16x16x32_bf16 v[120:123], v[140:143], v[148:151], v[120:123]
	v_mfma_f32_16x16x32_bf16 v[116:119], v[132:135], v[166:169], v[116:119]
	v_mfma_f32_16x16x32_bf16 v[112:115], v[140:143], v[166:169], v[112:115]
	v_mfma_f32_16x16x32_bf16 v[108:111], v[132:135], v[174:177], v[108:111]
	v_mfma_f32_16x16x32_bf16 v[104:107], v[140:143], v[174:177], v[104:107]
	v_mfma_f32_16x16x32_bf16 v[100:103], v[132:135], v[182:185], v[100:103]
	v_mfma_f32_16x16x32_bf16 v[96:99], v[140:143], v[182:185], v[96:99]
	v_mfma_f32_16x16x32_bf16 v[92:95], v[186:189], v[144:147], 0
	v_mfma_f32_16x16x32_bf16 v[88:91], v[194:197], v[144:147], 0
	v_mfma_f32_16x16x32_bf16 v[84:87], v[186:189], v[162:165], 0
	v_mfma_f32_16x16x32_bf16 v[80:83], v[194:197], v[162:165], 0
	v_mfma_f32_16x16x32_bf16 v[76:79], v[186:189], v[170:173], 0
	v_mfma_f32_16x16x32_bf16 v[72:75], v[194:197], v[170:173], 0
	v_mfma_f32_16x16x32_bf16 v[68:71], v[186:189], v[178:181], 0
	v_mfma_f32_16x16x32_bf16 v[64:67], v[194:197], v[178:181], 0
	v_mfma_f32_16x16x32_bf16 v[92:95], v[190:193], v[148:151], v[92:95]
	v_mfma_f32_16x16x32_bf16 v[88:91], v[198:201], v[148:151], v[88:91]
	v_mfma_f32_16x16x32_bf16 v[84:87], v[190:193], v[166:169], v[84:87]
	v_mfma_f32_16x16x32_bf16 v[80:83], v[198:201], v[166:169], v[80:83]
	v_mfma_f32_16x16x32_bf16 v[76:79], v[190:193], v[174:177], v[76:79]
	v_mfma_f32_16x16x32_bf16 v[72:75], v[198:201], v[174:177], v[72:75]
	v_mfma_f32_16x16x32_bf16 v[68:71], v[190:193], v[182:185], v[68:71]
	v_mfma_f32_16x16x32_bf16 v[64:67], v[198:201], v[182:185], v[64:67]
	s_barrier
	s_mov_b32 m0, s55
	v_lshl_add_u64 v[202:203], s[24:25], 0, v[152:153]
	global_load_lds_dwordx4 v[202:203], off
	s_add_i32 m0, s55, 0x2000
	v_lshl_add_u64 v[202:203], s[24:25], 0, v[156:157]
	global_load_lds_dwordx4 v[202:203], off
	s_mov_b32 m0, s33
	v_lshl_add_u64 v[202:203], s[26:27], 0, v[152:153]
	global_load_lds_dwordx4 v[202:203], off nt
	s_mov_b32 m0, s34
	v_lshl_add_u64 v[202:203], s[26:27], 0, v[156:157]
	global_load_lds_dwordx4 v[202:203], off nt
	s_add_u32 s56, s24, s52
	s_addc_u32 s57, s25, 0
	s_add_i32 s55, s58, s31
	s_mov_b32 m0, s55
	v_lshl_add_u64 v[202:203], s[56:57], 0, v[152:153]
	global_load_lds_dwordx4 v[202:203], off
	s_add_i32 m0, s55, 0x2000
	v_lshl_add_u64 v[202:203], s[56:57], 0, v[156:157]
	global_load_lds_dwordx4 v[202:203], off
	ds_read_b128 v[144:147], v209 offset:16384
	ds_read_b128 v[162:165], v209 offset:18432
	ds_read_b128 v[170:173], v209 offset:20480
	ds_read_b128 v[178:181], v209 offset:22528
	ds_read_b128 v[148:151], v209 offset:17408
	ds_read_b128 v[166:169], v209 offset:19456
	ds_read_b128 v[174:177], v209 offset:21504
	ds_read_b128 v[182:185], v209 offset:23552
	s_waitcnt vmcnt(6)
	s_waitcnt lgkmcnt(0)
	s_barrier
; #define PG8_STAGE(bufoff, gbase, voff) do { _Pragma("unroll") for (int _i = 0; _i < 2; ++_i) \
;         __builtin_amdgcn_global_load_lds((const unsigned*)((const char*)(gbase) + (voff)[_i]), (LAS unsigned*)(lds + (bufoff) + ldsw + _i * 8192), 16, 0, 0); } while (0)
; #define PG8_LDA(dst, b, h) do { _Pragma("unroll") for (int m = 0; m < 4; ++m) _Pragma("unroll") for (int k = 0; k < 2; ++k) dst[m][k] = *(const LAS bf16x8*)(lds + PG8_SA(b, h) + aoff + m * 2048 + k * 1024); } while (0)
; #define PG8_LDB(dst, b, h) do { _Pragma("unroll") for (int n = 0; n < 2; ++n) _Pragma("unroll") for (int k = 0; k < 2; ++k) dst[n][k] = *(const LAS bf16x8*)(lds + PG8_SB(b, h) + boff + n * 2048 + k * 1024); } while (0)
; #define PG8_WAIT_V(n) asm volatile("s_waitcnt vmcnt(" #n ")" ::: "memory")
; #define PG8_WAIT_L(n) asm volatile("s_waitcnt lgkmcnt(" #n ")" ::: "memory")
; #define PG8_BAR __builtin_amdgcn_s_barrier()
; #define PG8_SCHED __builtin_amdgcn_sched_barrier(0)
; template <class Epi>
; __device__ __forceinline__ void gemm_phase(LAS unsigned char* lds, const Gemm g, const StaticOrder& S, const Epi& E) {
;     ...
;             PG8_LDB(B0, 0, 0); PG8_SCHED; PG8_LDA(At, 0, 0); PG8_STAGE(PG8_SA(1, 1), a1 + hstepA, voffA);
;             PG8_WAIT_L(8); PG8_BAR; PG8_WAIT_L(0); PG8_MMA(0, 0, At, B0); PG8_BAR; PG8_SCHED;
;             PG8_LDB(B1, 0, 1); PG8_STAGE(PG8_SB(0, 0), b2, voffB);
;             PG8_BAR; PG8_WAIT_L(0); PG8_MMA(0, 1, At, B1); PG8_BAR;
;             PG8_LDA(At, 0, 1); PG8_STAGE(PG8_SA(0, 0), a2, voffA);
;             PG8_BAR; PG8_WAIT_L(0); PG8_MMA(1, 0, At, B0); PG8_BAR; PG8_SCHED;
;             PG8_STAGE(PG8_SB(0, 1), b2 + hstepB, voffB);
;             PG8_WAIT_V(6); PG8_BAR; PG8_MMA(1, 1, At, B1); PG8_BAR;
;             PG8_LDB(B0, 1, 0); PG8_SCHED; PG8_LDA(At, 1, 0); PG8_STAGE(PG8_SA(0, 1), a2 + hstepA, voffA);
;             PG8_WAIT_L(8); PG8_BAR; PG8_WAIT_L(0); PG8_MMA(0, 0, At, B0); PG8_BAR; PG8_SCHED;
;             PG8_LDB(B1, 1, 1); PG8_STAGE(PG8_SB(1, 0), b3, voffB);
;             PG8_BAR; PG8_WAIT_L(0); PG8_MMA(0, 1, At, B1); PG8_BAR;
;             PG8_LDA(At, 1, 1); PG8_STAGE(PG8_SA(1, 0), a3, voffA);
;             PG8_BAR; PG8_WAIT_L(0); PG8_MMA(1, 0, At, B0); PG8_BAR; PG8_SCHED;
;             PG8_STAGE(PG8_SB(1, 1), b3 + hstepB, voffB);
;             PG8_WAIT_V(6); PG8_BAR; PG8_MMA(1, 1, At, B1); PG8_BAR;
	v_mfma_f32_16x16x32_bf16 v[60:63], v[128:131], v[144:147], 0
	v_mfma_f32_16x16x32_bf16 v[56:59], v[136:139], v[144:147], 0
	v_mfma_f32_16x16x32_bf16 v[52:55], v[128:131], v[162:165], 0
	v_mfma_f32_16x16x32_bf16 v[48:51], v[136:139], v[162:165], 0
	v_mfma_f32_16x16x32_bf16 v[44:47], v[128:131], v[170:173], 0
	v_mfma_f32_16x16x32_bf16 v[40:43], v[136:139], v[170:173], 0
	v_mfma_f32_16x16x32_bf16 v[36:39], v[128:131], v[178:181], 0
	v_mfma_f32_16x16x32_bf16 v[32:35], v[136:139], v[178:181], 0
	v_mfma_f32_16x16x32_bf16 v[60:63], v[132:135], v[148:151], v[60:63]
	v_mfma_f32_16x16x32_bf16 v[56:59], v[140:143], v[148:151], v[56:59]
	v_mfma_f32_16x16x32_bf16 v[52:55], v[132:135], v[166:169], v[52:55]
	v_mfma_f32_16x16x32_bf16 v[48:51], v[140:143], v[166:169], v[48:51]
	v_mfma_f32_16x16x32_bf16 v[44:47], v[132:135], v[174:177], v[44:47]
	v_mfma_f32_16x16x32_bf16 v[40:43], v[140:143], v[174:177], v[40:43]
	v_mfma_f32_16x16x32_bf16 v[36:39], v[132:135], v[182:185], v[36:39]
	v_mfma_f32_16x16x32_bf16 v[32:35], v[140:143], v[182:185], v[32:35]
	v_mfma_f32_16x16x32_bf16 v[28:31], v[186:189], v[144:147], 0
	v_mfma_f32_16x16x32_bf16 v[24:27], v[194:197], v[144:147], 0
	s_add_i32 s55, 0, 0x18000
	v_add_u32_e32 v140, s55, v207
	v_mfma_f32_16x16x32_bf16 v[20:23], v[186:189], v[162:165], 0
	v_mfma_f32_16x16x32_bf16 v[16:19], v[194:197], v[162:165], 0
	v_mfma_f32_16x16x32_bf16 v[12:15], v[186:189], v[170:173], 0
	v_mfma_f32_16x16x32_bf16 v[8:11], v[194:197], v[170:173], 0
	v_mfma_f32_16x16x32_bf16 v[4:7], v[186:189], v[178:181], 0
	v_mfma_f32_16x16x32_bf16 v[0:3], v[194:197], v[178:181], 0
	v_mfma_f32_16x16x32_bf16 v[28:31], v[190:193], v[148:151], v[28:31]
	v_mfma_f32_16x16x32_bf16 v[24:27], v[198:201], v[148:151], v[24:27]
	v_mfma_f32_16x16x32_bf16 v[20:23], v[190:193], v[166:169], v[20:23]
	v_mfma_f32_16x16x32_bf16 v[16:19], v[198:201], v[166:169], v[16:19]
	v_mfma_f32_16x16x32_bf16 v[12:15], v[190:193], v[174:177], v[12:15]
	v_mfma_f32_16x16x32_bf16 v[8:11], v[198:201], v[174:177], v[8:11]
	v_mfma_f32_16x16x32_bf16 v[4:7], v[190:193], v[182:185], v[4:7]
	v_mfma_f32_16x16x32_bf16 v[0:3], v[198:201], v[182:185], v[0:3]
	s_barrier
	s_add_u32 s26, s26, s52
	s_addc_u32 s27, s27, 0
	s_mov_b32 m0, s35
	v_lshl_add_u64 v[186:187], s[26:27], 0, v[152:153]
	global_load_lds_dwordx4 v[186:187], off nt
	s_mov_b32 m0, s36
	v_lshl_add_u64 v[186:187], s[26:27], 0, v[156:157]
	global_load_lds_dwordx4 v[186:187], off nt
	ds_read_b128 v[128:131], v140
	ds_read_b128 v[136:139], v140 offset:2048
	ds_read_b128 v[132:135], v140 offset:1024
	ds_read_b128 v[140:143], v140 offset:3072
	ds_read_b128 v[144:147], v209 offset:32768
	ds_read_b128 v[162:165], v209 offset:34816
	ds_read_b128 v[170:173], v209 offset:36864
	ds_read_b128 v[178:181], v209 offset:38912
	ds_read_b128 v[148:151], v209 offset:33792
	ds_read_b128 v[166:169], v209 offset:35840
	ds_read_b128 v[174:177], v209 offset:37888
	ds_read_b128 v[182:185], v209 offset:39936
	s_mov_b32 s26, 0x1c000
	s_add_u32 s24, s24, 0x4000
	s_addc_u32 s25, s25, 0
	s_add_i32 s27, s55, s31
	v_add_u32_e32 v198, s26, v207
	ds_read_b128 v[186:189], v198
	ds_read_b128 v[194:197], v198 offset:2048
	ds_read_b128 v[190:193], v198 offset:1024
	ds_read_b128 v[198:201], v198 offset:3072
	s_waitcnt lgkmcnt(0)
	s_barrier
	v_mfma_f32_16x16x32_bf16 v[124:127], v[128:131], v[144:147], v[124:127]
	v_mfma_f32_16x16x32_bf16 v[120:123], v[136:139], v[144:147], v[120:123]
	v_mfma_f32_16x16x32_bf16 v[116:119], v[128:131], v[162:165], v[116:119]
	v_mfma_f32_16x16x32_bf16 v[112:115], v[136:139], v[162:165], v[112:115]
	v_mfma_f32_16x16x32_bf16 v[108:111], v[128:131], v[170:173], v[108:111]
	v_mfma_f32_16x16x32_bf16 v[104:107], v[136:139], v[170:173], v[104:107]
	v_mfma_f32_16x16x32_bf16 v[100:103], v[128:131], v[178:181], v[100:103]
	v_mfma_f32_16x16x32_bf16 v[96:99], v[136:139], v[178:181], v[96:99]
	v_mfma_f32_16x16x32_bf16 v[124:127], v[132:135], v[148:151], v[124:127]
	v_mfma_f32_16x16x32_bf16 v[120:123], v[140:143], v[148:151], v[120:123]
	v_mfma_f32_16x16x32_bf16 v[116:119], v[132:135], v[166:169], v[116:119]
	v_mfma_f32_16x16x32_bf16 v[112:115], v[140:143], v[166:169], v[112:115]
	v_mfma_f32_16x16x32_bf16 v[108:111], v[132:135], v[174:177], v[108:111]
	v_mfma_f32_16x16x32_bf16 v[104:107], v[140:143], v[174:177], v[104:107]
	v_mfma_f32_16x16x32_bf16 v[100:103], v[132:135], v[182:185], v[100:103]
	v_mfma_f32_16x16x32_bf16 v[96:99], v[140:143], v[182:185], v[96:99]
	v_mfma_f32_16x16x32_bf16 v[92:95], v[186:189], v[144:147], v[92:95]
	v_mfma_f32_16x16x32_bf16 v[88:91], v[194:197], v[144:147], v[88:91]
	v_mfma_f32_16x16x32_bf16 v[84:87], v[186:189], v[162:165], v[84:87]
	v_mfma_f32_16x16x32_bf16 v[80:83], v[194:197], v[162:165], v[80:83]
	v_mfma_f32_16x16x32_bf16 v[76:79], v[186:189], v[170:173], v[76:79]
	v_mfma_f32_16x16x32_bf16 v[72:75], v[194:197], v[170:173], v[72:75]
	v_mfma_f32_16x16x32_bf16 v[68:71], v[186:189], v[178:181], v[68:71]
	v_mfma_f32_16x16x32_bf16 v[64:67], v[194:197], v[178:181], v[64:67]
	v_mfma_f32_16x16x32_bf16 v[92:95], v[190:193], v[148:151], v[92:95]
	v_mfma_f32_16x16x32_bf16 v[88:91], v[198:201], v[148:151], v[88:91]
	v_mfma_f32_16x16x32_bf16 v[84:87], v[190:193], v[166:169], v[84:87]
	v_mfma_f32_16x16x32_bf16 v[80:83], v[198:201], v[166:169], v[80:83]
	v_mfma_f32_16x16x32_bf16 v[76:79], v[190:193], v[174:177], v[76:79]
	v_mfma_f32_16x16x32_bf16 v[72:75], v[198:201], v[174:177], v[72:75]
	v_mfma_f32_16x16x32_bf16 v[68:71], v[190:193], v[182:185], v[68:71]
	v_mfma_f32_16x16x32_bf16 v[64:67], v[198:201], v[182:185], v[64:67]
	s_barrier
; #define PG8_STAGE(bufoff, gbase, voff) do { _Pragma("unroll") for (int _i = 0; _i < 2; ++_i) \
;         __builtin_amdgcn_global_load_lds((const unsigned*)((const char*)(gbase) + (voff)[_i]), (LAS unsigned*)(lds + (bufoff) + ldsw + _i * 8192), 16, 0, 0); } while (0)
; #define PG8_LDA(dst, b, h) do { _Pragma("unroll") for (int m = 0; m < 4; ++m) _Pragma("unroll") for (int k = 0; k < 2; ++k) dst[m][k] = *(const LAS bf16x8*)(lds + PG8_SA(b, h) + aoff + m * 2048 + k * 1024); } while (0)
; #define PG8_WAIT_V(n) asm volatile("s_waitcnt vmcnt(" #n ")" ::: "memory")
; #define PG8_WAIT_L(n) asm volatile("s_waitcnt lgkmcnt(" #n ")" ::: "memory")
; template <class Epi>
; __device__ __forceinline__ void gemm_phase(LAS unsigned char* lds, const Gemm g, const StaticOrder& S, const Epi& E) {
;     ...
;         for (int t = 0; t < nt; t += 2) {
;             const bool last = (t == nt - 2);
;             const char* a1 = cA + (size_t)(t + 1) * kstep;
;             const char* a2 = last ? nA : cA + (size_t)(t + 2) * kstep; const char* b2 = last ? nB : cB + (size_t)(t + 2) * kstep;
;             const char* a3 = a2 + kstep; const char* b3 = b2 + kstep;
;             PG8_LDB(B0, 0, 0); PG8_SCHED; PG8_LDA(At, 0, 0); PG8_STAGE(PG8_SA(1, 1), a1 + hstepA, voffA);
;             PG8_WAIT_L(8); PG8_BAR; PG8_WAIT_L(0); PG8_MMA(0, 0, At, B0); PG8_BAR; PG8_SCHED;
;             PG8_LDB(B1, 0, 1); PG8_STAGE(PG8_SB(0, 0), b2, voffB);
;             PG8_BAR; PG8_WAIT_L(0); PG8_MMA(0, 1, At, B1); PG8_BAR;
;             PG8_LDA(At, 0, 1); PG8_STAGE(PG8_SA(0, 0), a2, voffA);
;             PG8_BAR; PG8_WAIT_L(0); PG8_MMA(1, 0, At, B0); PG8_BAR; PG8_SCHED;
;             PG8_STAGE(PG8_SB(0, 1), b2 + hstepB, voffB);
;             PG8_WAIT_V(6); PG8_BAR; PG8_MMA(1, 1, At, B1); PG8_BAR;
;             PG8_LDB(B0, 1, 0); PG8_SCHED; PG8_LDA(At, 1, 0); PG8_STAGE(PG8_SA(0, 1), a2 + hstepA, voffA);
;             PG8_WAIT_L(8); PG8_BAR; PG8_WAIT_L(0); PG8_MMA(0, 0, At, B0); PG8_BAR; PG8_SCHED;
;             PG8_LDB(B1, 1, 1); PG8_STAGE(PG8_SB(1, 0), b3, voffB);
;             PG8_BAR; PG8_WAIT_L(0); PG8_MMA(0, 1, At, B1); PG8_BAR;
;             PG8_LDA(At, 1, 1); PG8_STAGE(PG8_SA(1, 0), a3, voffA);
;             PG8_BAR; PG8_WAIT_L(0); PG8_MMA(1, 0, At, B0); PG8_BAR; PG8_SCHED;
;             PG8_STAGE(PG8_SB(1, 1), b3 + hstepB, voffB);
;             PG8_WAIT_V(6); PG8_BAR; PG8_MMA(1, 1, At, B1); PG8_BAR;
	s_mov_b32 m0, s27
	v_lshl_add_u64 v[202:203], s[24:25], 0, v[152:153]
	global_load_lds_dwordx4 v[202:203], off
	s_add_i32 m0, s27, 0x2000
	v_lshl_add_u64 v[202:203], s[24:25], 0, v[156:157]
	global_load_lds_dwordx4 v[202:203], off
	s_mov_b32 m0, s38
	v_lshl_add_u64 v[202:203], s[22:23], 0, v[152:153]
	global_load_lds_dwordx4 v[202:203], off nt
	s_mov_b32 m0, s39
	v_lshl_add_u64 v[202:203], s[22:23], 0, v[156:157]
	global_load_lds_dwordx4 v[202:203], off nt
	s_add_u32 s22, s24, s52
	s_addc_u32 s23, s25, 0
	s_add_i32 s24, s26, s31
	s_mov_b32 m0, s24
	v_lshl_add_u64 v[202:203], s[22:23], 0, v[152:153]
	global_load_lds_dwordx4 v[202:203], off
	s_add_i32 m0, s24, 0x2000
	v_lshl_add_u64 v[202:203], s[22:23], 0, v[156:157]
	global_load_lds_dwordx4 v[202:203], off
	ds_read_b128 v[144:147], v209 offset:49152
	ds_read_b128 v[162:165], v209 offset:51200
	ds_read_b128 v[170:173], v209 offset:53248
	ds_read_b128 v[178:181], v209 offset:55296
	ds_read_b128 v[148:151], v209 offset:50176
	ds_read_b128 v[166:169], v209 offset:52224
	ds_read_b128 v[174:177], v209 offset:54272
	ds_read_b128 v[182:185], v209 offset:56320
	s_waitcnt vmcnt(6)
	s_waitcnt lgkmcnt(0)
	s_barrier
	v_mfma_f32_16x16x32_bf16 v[60:63], v[128:131], v[144:147], v[60:63]
	v_mfma_f32_16x16x32_bf16 v[56:59], v[136:139], v[144:147], v[56:59]
	v_mfma_f32_16x16x32_bf16 v[52:55], v[128:131], v[162:165], v[52:55]
	v_mfma_f32_16x16x32_bf16 v[48:51], v[136:139], v[162:165], v[48:51]
	v_mfma_f32_16x16x32_bf16 v[44:47], v[128:131], v[170:173], v[44:47]
	v_mfma_f32_16x16x32_bf16 v[40:43], v[136:139], v[170:173], v[40:43]
	v_mfma_f32_16x16x32_bf16 v[36:39], v[128:131], v[178:181], v[36:39]
	v_mfma_f32_16x16x32_bf16 v[32:35], v[136:139], v[178:181], v[32:35]
	v_mfma_f32_16x16x32_bf16 v[60:63], v[132:135], v[148:151], v[60:63]
	v_mfma_f32_16x16x32_bf16 v[56:59], v[140:143], v[148:151], v[56:59]
	v_mfma_f32_16x16x32_bf16 v[52:55], v[132:135], v[166:169], v[52:55]
	v_mfma_f32_16x16x32_bf16 v[48:51], v[140:143], v[166:169], v[48:51]
	v_mfma_f32_16x16x32_bf16 v[44:47], v[132:135], v[174:177], v[44:47]
	v_mfma_f32_16x16x32_bf16 v[40:43], v[140:143], v[174:177], v[40:43]
	v_mfma_f32_16x16x32_bf16 v[36:39], v[132:135], v[182:185], v[36:39]
	v_mfma_f32_16x16x32_bf16 v[32:35], v[140:143], v[182:185], v[32:35]
	v_mfma_f32_16x16x32_bf16 v[28:31], v[186:189], v[144:147], v[28:31]
	v_mfma_f32_16x16x32_bf16 v[24:27], v[194:197], v[144:147], v[24:27]
	s_add_u32 s4, s4, 0x8000
	s_addc_u32 s5, s5, 0
	s_add_u32 s50, s50, 0x8000
	s_addc_u32 s51, s51, 0
	v_mfma_f32_16x16x32_bf16 v[20:23], v[186:189], v[162:165], v[20:23]
	v_mfma_f32_16x16x32_bf16 v[16:19], v[194:197], v[162:165], v[16:19]
	v_mfma_f32_16x16x32_bf16 v[12:15], v[186:189], v[170:173], v[12:15]
	v_mfma_f32_16x16x32_bf16 v[8:11], v[194:197], v[170:173], v[8:11]
	v_mfma_f32_16x16x32_bf16 v[4:7], v[186:189], v[178:181], v[4:7]
	v_mfma_f32_16x16x32_bf16 v[0:3], v[194:197], v[178:181], v[0:3]
	v_mfma_f32_16x16x32_bf16 v[28:31], v[190:193], v[148:151], v[28:31]
	v_mfma_f32_16x16x32_bf16 v[24:27], v[198:201], v[148:151], v[24:27]
	v_mfma_f32_16x16x32_bf16 v[20:23], v[190:193], v[166:169], v[20:23]
	v_mfma_f32_16x16x32_bf16 v[16:19], v[198:201], v[166:169], v[16:19]
	v_mfma_f32_16x16x32_bf16 v[12:15], v[190:193], v[174:177], v[12:15]
	v_mfma_f32_16x16x32_bf16 v[8:11], v[198:201], v[174:177], v[8:11]
	v_mfma_f32_16x16x32_bf16 v[4:7], v[190:193], v[182:185], v[4:7]
	s_cmp_ge_u32 s54, s28
	s_mov_b32 s22, s54
	v_mfma_f32_16x16x32_bf16 v[0:3], v[198:201], v[182:185], v[0:3]
	s_barrier
	s_cbranch_scc0 .LBB0_187
	s_branch .Lpeel_done_187
.LBB0_187:
	s_add_i32 s54, s22, 2
	s_add_u32 s23, s4, 0x4000
	s_addc_u32 s24, s5, 0
	s_cmp_eq_u32 s40, s22
	s_cselect_b32 s26, s6, s23
	s_cselect_b32 s27, s7, s24
	s_cselect_b32 s24, s20, s50
	s_cselect_b32 s25, s21, s51
	s_add_u32 s22, s26, 0x4000
	s_addc_u32 s23, s27, 0
	s_add_i32 m0, s33, 0xc000
	v_lshl_add_u64 v[186:187], s[4:5], 0, v[158:159]
	global_load_lds_dwordx4 v[186:187], off nt
	s_add_i32 m0, s33, 0xe000
	v_lshl_add_u64 v[186:187], s[4:5], 0, v[160:161]
	global_load_lds_dwordx4 v[186:187], off nt
	s_mov_b32 s55, 0x10000
	v_add_u32_e32 v140, s55, v207
	ds_read_b128 v[128:131], v140
	ds_read_b128 v[136:139], v140 offset:2048
	ds_read_b128 v[132:135], v140 offset:1024
	ds_read_b128 v[140:143], v140 offset:3072
	ds_read_b128 v[144:147], v209
	ds_read_b128 v[162:165], v209 offset:2048
	ds_read_b128 v[170:173], v209 offset:4096
	ds_read_b128 v[178:181], v209 offset:6144
	ds_read_b128 v[148:151], v209 offset:1024
	ds_read_b128 v[166:169], v209 offset:3072
	ds_read_b128 v[174:177], v209 offset:5120
	ds_read_b128 v[182:185], v209 offset:7168
	s_mov_b32 s58, 0x14000
	s_add_i32 s55, s55, s31
	v_add_u32_e32 v198, s58, v207
	ds_read_b128 v[186:189], v198
	ds_read_b128 v[194:197], v198 offset:2048
	ds_read_b128 v[190:193], v198 offset:1024
	ds_read_b128 v[198:201], v198 offset:3072
	s_waitcnt lgkmcnt(0)
	s_barrier
; #define PG8_STAGE(bufoff, gbase, voff) do { _Pragma("unroll") for (int _i = 0; _i < 2; ++_i) \
;         __builtin_amdgcn_global_load_lds((const unsigned*)((const char*)(gbase) + (voff)[_i]), (LAS unsigned*)(lds + (bufoff) + ldsw + _i * 8192), 16, 0, 0); } while (0)
; #define PG8_LDA(dst, b, h) do { _Pragma("unroll") for (int m = 0; m < 4; ++m) _Pragma("unroll") for (int k = 0; k < 2; ++k) dst[m][k] = *(const LAS bf16x8*)(lds + PG8_SA(b, h) + aoff + m * 2048 + k * 1024); } while (0)
; #define PG8_LDB(dst, b, h) do { _Pragma("unroll") for (int n = 0; n < 2; ++n) _Pragma("unroll") for (int k = 0; k < 2; ++k) dst[n][k] = *(const LAS bf16x8*)(lds + PG8_SB(b, h) + boff + n * 2048 + k * 1024); } while (0)
; #define PG8_WAIT_V(n) asm volatile("s_waitcnt vmcnt(" #n ")" ::: "memory")
; #define PG8_WAIT_L(n) asm volatile("s_waitcnt lgkmcnt(" #n ")" ::: "memory")
; #define PG8_BAR __builtin_amdgcn_s_barrier()
; #define PG8_SCHED __builtin_amdgcn_sched_barrier(0)
; template <class Epi>
; __device__ __forceinline__ void gemm_phase(LAS unsigned char* lds, const Gemm g, const StaticOrder& S, const Epi& E) {
;     ...
;             PG8_LDB(B0, 0, 0); PG8_SCHED; PG8_LDA(At, 0, 0); PG8_STAGE(PG8_SA(1, 1), a1 + hstepA, voffA);
;             PG8_WAIT_L(8); PG8_BAR; PG8_WAIT_L(0); PG8_MMA(0, 0, At, B0); PG8_BAR; PG8_SCHED;
;             PG8_LDB(B1, 0, 1); PG8_STAGE(PG8_SB(0, 0), b2, voffB);
;             PG8_BAR; PG8_WAIT_L(0); PG8_MMA(0, 1, At, B1); PG8_BAR;
;             PG8_LDA(At, 0, 1); PG8_STAGE(PG8_SA(0, 0), a2, voffA);
;             PG8_BAR; PG8_WAIT_L(0); PG8_MMA(1, 0, At, B0); PG8_BAR; PG8_SCHED;
;             PG8_STAGE(PG8_SB(0, 1), b2 + hstepB, voffB);
;             PG8_WAIT_V(6); PG8_BAR; PG8_MMA(1, 1, At, B1); PG8_BAR;
;             PG8_LDB(B0, 1, 0); PG8_SCHED; PG8_LDA(At, 1, 0); PG8_STAGE(PG8_SA(0, 1), a2 + hstepA, voffA);
;             PG8_WAIT_L(8); PG8_BAR; PG8_WAIT_L(0); PG8_MMA(0, 0, At, B0); PG8_BAR; PG8_SCHED;
;             PG8_LDB(B1, 1, 1); PG8_STAGE(PG8_SB(1, 0), b3, voffB);
;             PG8_BAR; PG8_WAIT_L(0); PG8_MMA(0, 1, At, B1); PG8_BAR;
;             PG8_LDA(At, 1, 1); PG8_STAGE(PG8_SA(1, 0), a3, voffA);
;             PG8_BAR; PG8_WAIT_L(0); PG8_MMA(1, 0, At, B0); PG8_BAR; PG8_SCHED;
;             PG8_STAGE(PG8_SB(1, 1), b3 + hstepB, voffB);
;             PG8_WAIT_V(6); PG8_BAR; PG8_MMA(1, 1, At, B1); PG8_BAR;
	v_mfma_f32_16x16x32_bf16 v[124:127], v[128:131], v[144:147], v[124:127]
	v_mfma_f32_16x16x32_bf16 v[120:123], v[136:139], v[144:147], v[120:123]
	v_mfma_f32_16x16x32_bf16 v[116:119], v[128:131], v[162:165], v[116:119]
	v_mfma_f32_16x16x32_bf16 v[112:115], v[136:139], v[162:165], v[112:115]
	v_mfma_f32_16x16x32_bf16 v[108:111], v[128:131], v[170:173], v[108:111]
	v_mfma_f32_16x16x32_bf16 v[104:107], v[136:139], v[170:173], v[104:107]
	v_mfma_f32_16x16x32_bf16 v[100:103], v[128:131], v[178:181], v[100:103]
	v_mfma_f32_16x16x32_bf16 v[96:99], v[136:139], v[178:181], v[96:99]
	v_mfma_f32_16x16x32_bf16 v[124:127], v[132:135], v[148:151], v[124:127]
	v_mfma_f32_16x16x32_bf16 v[120:123], v[140:143], v[148:151], v[120:123]
	v_mfma_f32_16x16x32_bf16 v[116:119], v[132:135], v[166:169], v[116:119]
	v_mfma_f32_16x16x32_bf16 v[112:115], v[140:143], v[166:169], v[112:115]
	v_mfma_f32_16x16x32_bf16 v[108:111], v[132:135], v[174:177], v[108:111]
	v_mfma_f32_16x16x32_bf16 v[104:107], v[140:143], v[174:177], v[104:107]
	v_mfma_f32_16x16x32_bf16 v[100:103], v[132:135], v[182:185], v[100:103]
	v_mfma_f32_16x16x32_bf16 v[96:99], v[140:143], v[182:185], v[96:99]
	v_mfma_f32_16x16x32_bf16 v[92:95], v[186:189], v[144:147], v[92:95]
	v_mfma_f32_16x16x32_bf16 v[88:91], v[194:197], v[144:147], v[88:91]
	v_mfma_f32_16x16x32_bf16 v[84:87], v[186:189], v[162:165], v[84:87]
	v_mfma_f32_16x16x32_bf16 v[80:83], v[194:197], v[162:165], v[80:83]
	v_mfma_f32_16x16x32_bf16 v[76:79], v[186:189], v[170:173], v[76:79]
	v_mfma_f32_16x16x32_bf16 v[72:75], v[194:197], v[170:173], v[72:75]
	v_mfma_f32_16x16x32_bf16 v[68:71], v[186:189], v[178:181], v[68:71]
	v_mfma_f32_16x16x32_bf16 v[64:67], v[194:197], v[178:181], v[64:67]
	v_mfma_f32_16x16x32_bf16 v[92:95], v[190:193], v[148:151], v[92:95]
	v_mfma_f32_16x16x32_bf16 v[88:91], v[198:201], v[148:151], v[88:91]
	v_mfma_f32_16x16x32_bf16 v[84:87], v[190:193], v[166:169], v[84:87]
	v_mfma_f32_16x16x32_bf16 v[80:83], v[198:201], v[166:169], v[80:83]
	v_mfma_f32_16x16x32_bf16 v[76:79], v[190:193], v[174:177], v[76:79]
	v_mfma_f32_16x16x32_bf16 v[72:75], v[198:201], v[174:177], v[72:75]
	v_mfma_f32_16x16x32_bf16 v[68:71], v[190:193], v[182:185], v[68:71]
	v_mfma_f32_16x16x32_bf16 v[64:67], v[198:201], v[182:185], v[64:67]
	s_barrier
	s_mov_b32 m0, s55
	v_lshl_add_u64 v[202:203], s[24:25], 0, v[152:153]
	global_load_lds_dwordx4 v[202:203], off
	s_add_i32 m0, s55, 0x2000
	v_lshl_add_u64 v[202:203], s[24:25], 0, v[156:157]
	global_load_lds_dwordx4 v[202:203], off
	s_mov_b32 m0, s33
	v_lshl_add_u64 v[202:203], s[26:27], 0, v[152:153]
	global_load_lds_dwordx4 v[202:203], off nt
	s_mov_b32 m0, s34
	v_lshl_add_u64 v[202:203], s[26:27], 0, v[156:157]
	global_load_lds_dwordx4 v[202:203], off nt
	s_add_u32 s56, s24, s52
	s_addc_u32 s57, s25, 0
	s_add_i32 s55, s58, s31
	s_mov_b32 m0, s55
	v_lshl_add_u64 v[202:203], s[56:57], 0, v[152:153]
	global_load_lds_dwordx4 v[202:203], off
	s_add_i32 m0, s55, 0x2000
	v_lshl_add_u64 v[202:203], s[56:57], 0, v[156:157]
	global_load_lds_dwordx4 v[202:203], off
	ds_read_b128 v[144:147], v209 offset:16384
	ds_read_b128 v[162:165], v209 offset:18432
	ds_read_b128 v[170:173], v209 offset:20480
	ds_read_b128 v[178:181], v209 offset:22528
	ds_read_b128 v[148:151], v209 offset:17408
	ds_read_b128 v[166:169], v209 offset:19456
	ds_read_b128 v[174:177], v209 offset:21504
	ds_read_b128 v[182:185], v209 offset:23552
	s_waitcnt vmcnt(6)
	s_waitcnt lgkmcnt(0)
	s_barrier
	v_mfma_f32_16x16x32_bf16 v[60:63], v[128:131], v[144:147], v[60:63]
	v_mfma_f32_16x16x32_bf16 v[56:59], v[136:139], v[144:147], v[56:59]
	v_mfma_f32_16x16x32_bf16 v[52:55], v[128:131], v[162:165], v[52:55]
	v_mfma_f32_16x16x32_bf16 v[48:51], v[136:139], v[162:165], v[48:51]
	v_mfma_f32_16x16x32_bf16 v[44:47], v[128:131], v[170:173], v[44:47]
	v_mfma_f32_16x16x32_bf16 v[40:43], v[136:139], v[170:173], v[40:43]
	v_mfma_f32_16x16x32_bf16 v[36:39], v[128:131], v[178:181], v[36:39]
	v_mfma_f32_16x16x32_bf16 v[32:35], v[136:139], v[178:181], v[32:35]
	v_mfma_f32_16x16x32_bf16 v[60:63], v[132:135], v[148:151], v[60:63]
	v_mfma_f32_16x16x32_bf16 v[56:59], v[140:143], v[148:151], v[56:59]
	v_mfma_f32_16x16x32_bf16 v[52:55], v[132:135], v[166:169], v[52:55]
	v_mfma_f32_16x16x32_bf16 v[48:51], v[140:143], v[166:169], v[48:51]
	v_mfma_f32_16x16x32_bf16 v[44:47], v[132:135], v[174:177], v[44:47]
	v_mfma_f32_16x16x32_bf16 v[40:43], v[140:143], v[174:177], v[40:43]
	v_mfma_f32_16x16x32_bf16 v[36:39], v[132:135], v[182:185], v[36:39]
	v_mfma_f32_16x16x32_bf16 v[32:35], v[140:143], v[182:185], v[32:35]
	v_mfma_f32_16x16x32_bf16 v[28:31], v[186:189], v[144:147], v[28:31]
	v_mfma_f32_16x16x32_bf16 v[24:27], v[194:197], v[144:147], v[24:27]
	s_add_i32 s55, 0, 0x18000
	v_add_u32_e32 v140, s55, v207
	v_mfma_f32_16x16x32_bf16 v[20:23], v[186:189], v[162:165], v[20:23]
	v_mfma_f32_16x16x32_bf16 v[16:19], v[194:197], v[162:165], v[16:19]
	v_mfma_f32_16x16x32_bf16 v[12:15], v[186:189], v[170:173], v[12:15]
	v_mfma_f32_16x16x32_bf16 v[8:11], v[194:197], v[170:173], v[8:11]
	v_mfma_f32_16x16x32_bf16 v[4:7], v[186:189], v[178:181], v[4:7]
	v_mfma_f32_16x16x32_bf16 v[0:3], v[194:197], v[178:181], v[0:3]
	v_mfma_f32_16x16x32_bf16 v[28:31], v[190:193], v[148:151], v[28:31]
	v_mfma_f32_16x16x32_bf16 v[24:27], v[198:201], v[148:151], v[24:27]
	v_mfma_f32_16x16x32_bf16 v[20:23], v[190:193], v[166:169], v[20:23]
	v_mfma_f32_16x16x32_bf16 v[16:19], v[198:201], v[166:169], v[16:19]
	v_mfma_f32_16x16x32_bf16 v[12:15], v[190:193], v[174:177], v[12:15]
	v_mfma_f32_16x16x32_bf16 v[8:11], v[198:201], v[174:177], v[8:11]
	v_mfma_f32_16x16x32_bf16 v[4:7], v[190:193], v[182:185], v[4:7]
	v_mfma_f32_16x16x32_bf16 v[0:3], v[198:201], v[182:185], v[0:3]
	s_barrier
; #define PG8_STAGE(bufoff, gbase, voff) do { _Pragma("unroll") for (int _i = 0; _i < 2; ++_i) \
;         __builtin_amdgcn_global_load_lds((const unsigned*)((const char*)(gbase) + (voff)[_i]), (LAS unsigned*)(lds + (bufoff) + ldsw + _i * 8192), 16, 0, 0); } while (0)
; #define PG8_LDA(dst, b, h) do { _Pragma("unroll") for (int m = 0; m < 4; ++m) _Pragma("unroll") for (int k = 0; k < 2; ++k) dst[m][k] = *(const LAS bf16x8*)(lds + PG8_SA(b, h) + aoff + m * 2048 + k * 1024); } while (0)
; #define PG8_LDB(dst, b, h) do { _Pragma("unroll") for (int n = 0; n < 2; ++n) _Pragma("unroll") for (int k = 0; k < 2; ++k) dst[n][k] = *(const LAS bf16x8*)(lds + PG8_SB(b, h) + boff + n * 2048 + k * 1024); } while (0)
; #define PG8_WAIT_V(n) asm volatile("s_waitcnt vmcnt(" #n ")" ::: "memory")
; #define PG8_WAIT_L(n) asm volatile("s_waitcnt lgkmcnt(" #n ")" ::: "memory")
; #define PG8_BAR __builtin_amdgcn_s_barrier()
; #define PG8_SCHED __builtin_amdgcn_sched_barrier(0)
; template <class Epi>
; __device__ __forceinline__ void gemm_phase(LAS unsigned char* lds, const Gemm g, const StaticOrder& S, const Epi& E) {
;     ...
;             PG8_LDB(B0, 0, 0); PG8_SCHED; PG8_LDA(At, 0, 0); PG8_STAGE(PG8_SA(1, 1), a1 + hstepA, voffA);
;             PG8_WAIT_L(8); PG8_BAR; PG8_WAIT_L(0); PG8_MMA(0, 0, At, B0); PG8_BAR; PG8_SCHED;
;             PG8_LDB(B1, 0, 1); PG8_STAGE(PG8_SB(0, 0), b2, voffB);
;             PG8_BAR; PG8_WAIT_L(0); PG8_MMA(0, 1, At, B1); PG8_BAR;
;             PG8_LDA(At, 0, 1); PG8_STAGE(PG8_SA(0, 0), a2, voffA);
;             PG8_BAR; PG8_WAIT_L(0); PG8_MMA(1, 0, At, B0); PG8_BAR; PG8_SCHED;
;             PG8_STAGE(PG8_SB(0, 1), b2 + hstepB, voffB);
;             PG8_WAIT_V(6); PG8_BAR; PG8_MMA(1, 1, At, B1); PG8_BAR;
;             PG8_LDB(B0, 1, 0); PG8_SCHED; PG8_LDA(At, 1, 0); PG8_STAGE(PG8_SA(0, 1), a2 + hstepA, voffA);
;             PG8_WAIT_L(8); PG8_BAR; PG8_WAIT_L(0); PG8_MMA(0, 0, At, B0); PG8_BAR; PG8_SCHED;
;             PG8_LDB(B1, 1, 1); PG8_STAGE(PG8_SB(1, 0), b3, voffB);
;             PG8_BAR; PG8_WAIT_L(0); PG8_MMA(0, 1, At, B1); PG8_BAR;
;             PG8_LDA(At, 1, 1); PG8_STAGE(PG8_SA(1, 0), a3, voffA);
;             PG8_BAR; PG8_WAIT_L(0); PG8_MMA(1, 0, At, B0); PG8_BAR; PG8_SCHED;
;             PG8_STAGE(PG8_SB(1, 1), b3 + hstepB, voffB);
;             PG8_WAIT_V(6); PG8_BAR; PG8_MMA(1, 1, At, B1); PG8_BAR;
	s_add_u32 s26, s26, s52
	s_addc_u32 s27, s27, 0
	s_mov_b32 m0, s35
	v_lshl_add_u64 v[186:187], s[26:27], 0, v[152:153]
	global_load_lds_dwordx4 v[186:187], off nt
	s_mov_b32 m0, s36
	v_lshl_add_u64 v[186:187], s[26:27], 0, v[156:157]
	global_load_lds_dwordx4 v[186:187], off nt
	ds_read_b128 v[128:131], v140
	ds_read_b128 v[136:139], v140 offset:2048
	ds_read_b128 v[132:135], v140 offset:1024
	ds_read_b128 v[140:143], v140 offset:3072
	ds_read_b128 v[144:147], v209 offset:32768
	ds_read_b128 v[162:165], v209 offset:34816
	ds_read_b128 v[170:173], v209 offset:36864
	ds_read_b128 v[178:181], v209 offset:38912
	ds_read_b128 v[148:151], v209 offset:33792
	ds_read_b128 v[166:169], v209 offset:35840
	ds_read_b128 v[174:177], v209 offset:37888
	ds_read_b128 v[182:185], v209 offset:39936
	s_mov_b32 s26, 0x1c000
	s_add_u32 s24, s24, 0x4000
	s_addc_u32 s25, s25, 0
	s_add_i32 s27, s55, s31
	v_add_u32_e32 v198, s26, v207
	ds_read_b128 v[186:189], v198
	ds_read_b128 v[194:197], v198 offset:2048
	ds_read_b128 v[190:193], v198 offset:1024
	ds_read_b128 v[198:201], v198 offset:3072
	s_waitcnt lgkmcnt(0)
	s_barrier
	v_mfma_f32_16x16x32_bf16 v[124:127], v[128:131], v[144:147], v[124:127]
	v_mfma_f32_16x16x32_bf16 v[120:123], v[136:139], v[144:147], v[120:123]
	v_mfma_f32_16x16x32_bf16 v[116:119], v[128:131], v[162:165], v[116:119]
	v_mfma_f32_16x16x32_bf16 v[112:115], v[136:139], v[162:165], v[112:115]
	v_mfma_f32_16x16x32_bf16 v[108:111], v[128:131], v[170:173], v[108:111]
	v_mfma_f32_16x16x32_bf16 v[104:107], v[136:139], v[170:173], v[104:107]
	v_mfma_f32_16x16x32_bf16 v[100:103], v[128:131], v[178:181], v[100:103]
	v_mfma_f32_16x16x32_bf16 v[96:99], v[136:139], v[178:181], v[96:99]
	v_mfma_f32_16x16x32_bf16 v[124:127], v[132:135], v[148:151], v[124:127]
	v_mfma_f32_16x16x32_bf16 v[120:123], v[140:143], v[148:151], v[120:123]
	v_mfma_f32_16x16x32_bf16 v[116:119], v[132:135], v[166:169], v[116:119]
	v_mfma_f32_16x16x32_bf16 v[112:115], v[140:143], v[166:169], v[112:115]
	v_mfma_f32_16x16x32_bf16 v[108:111], v[132:135], v[174:177], v[108:111]
	v_mfma_f32_16x16x32_bf16 v[104:107], v[140:143], v[174:177], v[104:107]
	v_mfma_f32_16x16x32_bf16 v[100:103], v[132:135], v[182:185], v[100:103]
	v_mfma_f32_16x16x32_bf16 v[96:99], v[140:143], v[182:185], v[96:99]
	v_mfma_f32_16x16x32_bf16 v[92:95], v[186:189], v[144:147], v[92:95]
	v_mfma_f32_16x16x32_bf16 v[88:91], v[194:197], v[144:147], v[88:91]
	v_mfma_f32_16x16x32_bf16 v[84:87], v[186:189], v[162:165], v[84:87]
	v_mfma_f32_16x16x32_bf16 v[80:83], v[194:197], v[162:165], v[80:83]
	v_mfma_f32_16x16x32_bf16 v[76:79], v[186:189], v[170:173], v[76:79]
	v_mfma_f32_16x16x32_bf16 v[72:75], v[194:197], v[170:173], v[72:75]
	v_mfma_f32_16x16x32_bf16 v[68:71], v[186:189], v[178:181], v[68:71]
	v_mfma_f32_16x16x32_bf16 v[64:67], v[194:197], v[178:181], v[64:67]
	v_mfma_f32_16x16x32_bf16 v[92:95], v[190:193], v[148:151], v[92:95]
	v_mfma_f32_16x16x32_bf16 v[88:91], v[198:201], v[148:151], v[88:91]
	v_mfma_f32_16x16x32_bf16 v[84:87], v[190:193], v[166:169], v[84:87]
	v_mfma_f32_16x16x32_bf16 v[80:83], v[198:201], v[166:169], v[80:83]
	v_mfma_f32_16x16x32_bf16 v[76:79], v[190:193], v[174:177], v[76:79]
	v_mfma_f32_16x16x32_bf16 v[72:75], v[198:201], v[174:177], v[72:75]
	v_mfma_f32_16x16x32_bf16 v[68:71], v[190:193], v[182:185], v[68:71]
	v_mfma_f32_16x16x32_bf16 v[64:67], v[198:201], v[182:185], v[64:67]
	s_barrier
	s_mov_b32 m0, s27
	v_lshl_add_u64 v[202:203], s[24:25], 0, v[152:153]
	global_load_lds_dwordx4 v[202:203], off
	s_add_i32 m0, s27, 0x2000
	v_lshl_add_u64 v[202:203], s[24:25], 0, v[156:157]
	global_load_lds_dwordx4 v[202:203], off
	s_mov_b32 m0, s38
	v_lshl_add_u64 v[202:203], s[22:23], 0, v[152:153]
	global_load_lds_dwordx4 v[202:203], off nt
	s_mov_b32 m0, s39
	v_lshl_add_u64 v[202:203], s[22:23], 0, v[156:157]
	global_load_lds_dwordx4 v[202:203], off nt
	s_add_u32 s22, s24, s52
	s_addc_u32 s23, s25, 0
	s_add_i32 s24, s26, s31
	s_mov_b32 m0, s24
	v_lshl_add_u64 v[202:203], s[22:23], 0, v[152:153]
	global_load_lds_dwordx4 v[202:203], off
	s_add_i32 m0, s24, 0x2000
	v_lshl_add_u64 v[202:203], s[22:23], 0, v[156:157]
	global_load_lds_dwordx4 v[202:203], off
	ds_read_b128 v[144:147], v209 offset:49152
	ds_read_b128 v[162:165], v209 offset:51200
	ds_read_b128 v[170:173], v209 offset:53248
	ds_read_b128 v[178:181], v209 offset:55296
	ds_read_b128 v[148:151], v209 offset:50176
	ds_read_b128 v[166:169], v209 offset:52224
	ds_read_b128 v[174:177], v209 offset:54272
	ds_read_b128 v[182:185], v209 offset:56320
	s_waitcnt vmcnt(6)
	s_waitcnt lgkmcnt(0)
	s_barrier
	v_mfma_f32_16x16x32_bf16 v[60:63], v[128:131], v[144:147], v[60:63]
	v_mfma_f32_16x16x32_bf16 v[56:59], v[136:139], v[144:147], v[56:59]
	v_mfma_f32_16x16x32_bf16 v[52:55], v[128:131], v[162:165], v[52:55]
	v_mfma_f32_16x16x32_bf16 v[48:51], v[136:139], v[162:165], v[48:51]
	v_mfma_f32_16x16x32_bf16 v[44:47], v[128:131], v[170:173], v[44:47]
	v_mfma_f32_16x16x32_bf16 v[40:43], v[136:139], v[170:173], v[40:43]
	v_mfma_f32_16x16x32_bf16 v[36:39], v[128:131], v[178:181], v[36:39]
	v_mfma_f32_16x16x32_bf16 v[32:35], v[136:139], v[178:181], v[32:35]
	v_mfma_f32_16x16x32_bf16 v[60:63], v[132:135], v[148:151], v[60:63]
	v_mfma_f32_16x16x32_bf16 v[56:59], v[140:143], v[148:151], v[56:59]
	v_mfma_f32_16x16x32_bf16 v[52:55], v[132:135], v[166:169], v[52:55]
	v_mfma_f32_16x16x32_bf16 v[48:51], v[140:143], v[166:169], v[48:51]
	v_mfma_f32_16x16x32_bf16 v[44:47], v[132:135], v[174:177], v[44:47]
	v_mfma_f32_16x16x32_bf16 v[40:43], v[140:143], v[174:177], v[40:43]
	v_mfma_f32_16x16x32_bf16 v[36:39], v[132:135], v[182:185], v[36:39]
	v_mfma_f32_16x16x32_bf16 v[32:35], v[140:143], v[182:185], v[32:35]
	v_mfma_f32_16x16x32_bf16 v[28:31], v[186:189], v[144:147], v[28:31]
	v_mfma_f32_16x16x32_bf16 v[24:27], v[194:197], v[144:147], v[24:27]
	s_add_u32 s4, s4, 0x8000
	s_addc_u32 s5, s5, 0
	s_add_u32 s50, s50, 0x8000
	s_addc_u32 s51, s51, 0
	v_mfma_f32_16x16x32_bf16 v[20:23], v[186:189], v[162:165], v[20:23]
	v_mfma_f32_16x16x32_bf16 v[16:19], v[194:197], v[162:165], v[16:19]
	v_mfma_f32_16x16x32_bf16 v[12:15], v[186:189], v[170:173], v[12:15]
	v_mfma_f32_16x16x32_bf16 v[8:11], v[194:197], v[170:173], v[8:11]
	v_mfma_f32_16x16x32_bf16 v[4:7], v[186:189], v[178:181], v[4:7]
	v_mfma_f32_16x16x32_bf16 v[0:3], v[194:197], v[178:181], v[0:3]
	v_mfma_f32_16x16x32_bf16 v[28:31], v[190:193], v[148:151], v[28:31]
	v_mfma_f32_16x16x32_bf16 v[24:27], v[198:201], v[148:151], v[24:27]
	v_mfma_f32_16x16x32_bf16 v[20:23], v[190:193], v[166:169], v[20:23]
	v_mfma_f32_16x16x32_bf16 v[16:19], v[198:201], v[166:169], v[16:19]
	v_mfma_f32_16x16x32_bf16 v[12:15], v[190:193], v[174:177], v[12:15]
	v_mfma_f32_16x16x32_bf16 v[8:11], v[198:201], v[174:177], v[8:11]
	v_mfma_f32_16x16x32_bf16 v[4:7], v[190:193], v[182:185], v[4:7]
	s_cmp_ge_u32 s54, s28
	s_mov_b32 s22, s54
	v_mfma_f32_16x16x32_bf16 v[0:3], v[198:201], v[182:185], v[0:3]
	s_barrier
	s_cbranch_scc0 .LBB0_187

; #define PG8_WAIT_V(n) asm volatile("s_waitcnt vmcnt(" #n ")" ::: "memory")
; #define PG8_BAR __builtin_amdgcn_s_barrier()
; template <class Epi>
; __device__ __forceinline__ void gemm_phase(LAS unsigned char* lds, const Gemm g, const StaticOrder& S, const Epi& E) {
;     ...
;     PG8_WAIT_V(0);
;     if (wr == 0) PG8_BAR;
;     PG8_BAR;
.LBB0_220:
	s_waitcnt vmcnt(0)
	s_setprio 0
	s_cmpk_gt_u32 s29, 0xff
	s_cbranch_scc1 .LBB0_222
	s_barrier

; #define PG8_STAGE(bufoff, gbase, voff) do { _Pragma("unroll") for (int _i = 0; _i < 2; ++_i) \
;         __builtin_amdgcn_global_load_lds((const unsigned*)((const char*)(gbase) + (voff)[_i]), (LAS unsigned*)(lds + (bufoff) + ldsw + _i * 8192), 16, 0, 0); } while (0)
; #define PG8_BAR __builtin_amdgcn_s_barrier()
;     __device__ bool next(int i, Unit& u) const {
;         const long L = (long)i * G + c; if (L >= nwg) return false;
;         int wgid = (int)L; { const int q = nwg / NXCD, r = nwg % NXCD, xcd = wgid % NXCD, off = wgid / NXCD; wgid = (xcd < r ? xcd * (q + 1) : r * (q + 1) + (xcd - r) * q) + off; }
;         const int nig = wgm * nN, gid = wgid / nig, fm = gid * wgm, gsz = (nM - fm) < wgm ? (nM - fm) : wgm;
;         u.pm = fm + ((wgid % nig) % gsz); u.pn = (wgid % nig) / gsz; return true;
; template <class Epi>
; __device__ __forceinline__ void gemm_phase(LAS unsigned char* lds, const Gemm g, const StaticOrder& S, const Epi& E) {
;     ...
;     const char* cA = (const char*)g.A + (size_t)cur.pm * tstepA; const char* cB = (const char*)g.Bt + (size_t)cur.pn * tstepB;
;     PG8_STAGE(PG8_SB(0, 0), cB, voffB); PG8_STAGE(PG8_SA(0, 0), cA, voffA); PG8_STAGE(PG8_SB(0, 1), cB + hstepB, voffB); PG8_STAGE(PG8_SA(0, 1), cA + hstepA, voffA);
;     if (wr == 1) PG8_BAR;
.LBB0_237:
	v_readlane_b32 s60, v253, 56
	v_readlane_b32 s0, v254, 41
	v_readlane_b32 s62, v253, 58
	v_readlane_b32 s63, v253, 59
	v_readlane_b32 s1, v254, 42
	v_readlane_b32 s64, v253, 60
	v_readlane_b32 s62, v254, 12
	v_readlane_b32 s36, v253, 24
	v_readlane_b32 s80, v254, 14
	v_readlane_b32 s82, v254, 16
	v_readlane_b32 s84, v254, 18
	v_readlane_b32 s88, v254, 20
	v_readlane_b32 s90, v254, 22
	v_readlane_b32 s92, v254, 24
	v_readlane_b32 s94, v254, 26
	v_readlane_b32 s96, v254, 28
	v_readlane_b32 s98, v254, 30
	v_readlane_b32 s24, v253, 40
	v_readlane_b32 s26, v253, 42
	v_readlane_b32 s28, v253, 44
	v_readlane_b32 s30, v253, 46
	v_readlane_b32 s34, v253, 48
	v_readlane_b32 s56, v253, 50
	v_readlane_b32 s58, v253, 52
	s_andn2_b64 vcc, exec, s[0:1]
	v_readlane_b32 s86, v253, 55
	v_readlane_b32 s61, v253, 57
	v_readlane_b32 s65, v253, 61
	v_readlane_b32 s66, v253, 62
	v_readlane_b32 s67, v253, 63
	v_readlane_b32 s68, v254, 0
	v_readlane_b32 s69, v254, 1
	v_readlane_b32 s70, v254, 2
	v_readlane_b32 s71, v254, 3
	v_readlane_b32 s72, v254, 4
	v_readlane_b32 s73, v254, 5
	v_readlane_b32 s74, v254, 6
	v_readlane_b32 s75, v254, 7
	v_readlane_b32 s78, v254, 10
	v_readlane_b32 s79, v254, 11
	v_readlane_b32 s63, v254, 13
	v_readlane_b32 s37, v253, 25
	v_readlane_b32 s38, v253, 26
	v_readlane_b32 s39, v253, 27
	v_readlane_b32 s40, v253, 28
	v_readlane_b32 s41, v253, 29
	v_readlane_b32 s42, v253, 30
	v_readlane_b32 s43, v253, 31
	v_readlane_b32 s44, v253, 32
	v_readlane_b32 s45, v253, 33
	v_readlane_b32 s46, v253, 34
	v_readlane_b32 s47, v253, 35
	v_readlane_b32 s48, v253, 36
	v_readlane_b32 s49, v253, 37
	v_readlane_b32 s50, v253, 38
	v_readlane_b32 s51, v253, 39
	v_readlane_b32 s81, v254, 15
	v_readlane_b32 s83, v254, 17
	v_readlane_b32 s85, v254, 19
	v_readlane_b32 s89, v254, 21
	v_readlane_b32 s91, v254, 23
	v_readlane_b32 s93, v254, 25
	v_readlane_b32 s95, v254, 27
	v_readlane_b32 s97, v254, 29
	v_readlane_b32 s99, v254, 31
	v_readlane_b32 s25, v253, 41
	v_readlane_b32 s27, v253, 43
	v_readlane_b32 s29, v253, 45
	v_readlane_b32 s31, v253, 47
	v_readlane_b32 s35, v253, 49
	v_readlane_b32 s57, v253, 51
	v_readlane_b32 s59, v253, 53
	s_mov_b32 s52, 0xc000
	s_movk_i32 s22, 0x3c0
	v_readlane_b32 s76, v254, 8
	v_readlane_b32 s77, v254, 9
	s_cbranch_vccnz .LBB0_314
	v_readlane_b32 s0, v254, 43
	s_cmp_eq_u32 s0, 1
	s_mov_b64 s[0:1], -1
	s_cbranch_scc1 .LBB0_256
	s_waitcnt vmcnt(0)
	v_mov_b32_e32 v0, v220
	v_readlane_b32 s0, v253, 19
	s_cmpk_gt_i32 s0, 0x5ff
	v_readfirstlane_b32 s20, v0
	s_cbranch_scc1 .LBB0_255
	s_cmpk_gt_u32 s20, 0xff
	s_cbranch_scc0 .Lprio_skip_s20
	s_setprio 1
.Lprio_skip_s20:
	v_readlane_b32 s2, v254, 36
	s_mul_i32 s1, s2, 0x1800000
	s_mul_hi_i32 s0, s2, 0x1800000
	s_add_u32 s21, s78, s1
	v_readlane_b32 s4, v253, 19
	s_addc_u32 s22, s79, s0
	s_ashr_i32 s24, s4, 31
	s_lshr_b32 s0, s24, 29
	v_readlane_b32 s3, v254, 37
	s_add_i32 s0, s4, s0
	s_ashr_i32 s2, s20, 6
	s_ashr_i32 s3, s0, 3
	s_and_b32 s0, s0, -8
	s_ashr_i32 s1, s20, 8
	s_lshl_b32 s23, s2, 10
	s_sub_i32 s0, s4, s0
	s_cmp_lt_i32 s0, 0
	s_movk_i32 s4, 0xc1
	s_cselect_b32 s4, s4, 0xc0
	s_mul_i32 s0, s0, s4
	s_add_i32 s0, s0, s3
	s_mul_hi_i32 s3, s0, 0x2aaaaaab
	s_lshr_b32 s4, s3, 31
	s_ashr_i32 s3, s3, 4
	s_add_i32 s3, s3, s4
	s_lshl_b32 s4, s3, 2
	s_mulk_i32 s3, 0x60
	s_sub_i32 s3, s0, s3
	s_bfe_i32 s0, s3, 0x80000
	s_bfe_u32 s0, s0, 0x2000d
	s_add_i32 s5, s3, s0
	s_bfe_i32 s0, s5, 0x80000
	s_and_b32 s5, s5, 0xfc
	s_sub_i32 s3, s3, s5
	s_sext_i32_i16 s0, s0
	s_sext_i32_i8 s3, s3
	s_lshr_b32 s0, s0, 2
	s_add_i32 s10, s4, s3
	s_ashr_i32 s11, s10, 31
	s_bfe_i64 s[6:7], s[0:1], 0x100000
	s_lshl_b64 s[4:5], s[10:11], 20
	s_lshl_b64 s[6:7], s[6:7], 20
	s_add_u32 s14, s21, s6
	s_addc_u32 s15, s22, s7
	s_add_i32 s25, s23, 0
	v_lshlrev_b32_e32 v156, 4, v0
	s_add_i32 m0, s25, 0x10000
	v_readlane_b32 s6, v252, 53
	global_load_lds_dwordx4 v156, s[14:15]
	s_add_i32 m0, s25, 0x12000
	v_add_u32_e32 v158, 0x2000, v156
	v_readlane_b32 s7, v252, 54
	s_add_u32 s12, s6, s4
	global_load_lds_dwordx4 v158, s[14:15]
	s_addc_u32 s13, s7, s5
	s_mov_b32 m0, s25
	s_add_i32 s26, s25, 0x2000
	global_load_lds_dwordx4 v156, s[12:13]
	s_mov_b32 m0, s26
	s_add_u32 s4, s14, 0x80000
	global_load_lds_dwordx4 v158, s[12:13]
	s_addc_u32 s5, s15, 0
	s_add_i32 m0, s25, 0x14000
	s_nop 0
	global_load_lds_dwordx4 v156, s[4:5]
	s_add_i32 m0, s25, 0x16000
	s_nop 0
	global_load_lds_dwordx4 v158, s[4:5]
	s_add_u32 s4, s12, 0x80000
	s_addc_u32 s5, s13, 0
	s_add_i32 s27, s25, 0x4000
	s_mov_b32 m0, s27
	s_add_i32 s28, s25, 0x6000
	global_load_lds_dwordx4 v156, s[4:5]
	s_mov_b32 m0, s28
	s_cmp_lg_u32 s1, 1
	global_load_lds_dwordx4 v158, s[4:5]
	s_cbranch_scc1 .LBB0_242
	s_barrier

; #define PG8_WAIT_V(n) asm volatile("s_waitcnt vmcnt(" #n ")" ::: "memory")
; #define PG8_BAR __builtin_amdgcn_s_barrier()
; template <class Epi>
; __device__ __forceinline__ void gemm_phase(LAS unsigned char* lds, const Gemm g, const StaticOrder& S, const Epi& E) {
;     ...
;     PG8_WAIT_V(0);
;     if (wr == 0) PG8_BAR;
;     PG8_BAR;
.LBB0_252:
	s_waitcnt vmcnt(0)
	v_readlane_b32 s24, v253, 40
	v_readlane_b32 s26, v253, 42
	v_readlane_b32 s28, v253, 44
	v_readlane_b32 s30, v253, 46
	v_readlane_b32 s34, v253, 48
	s_setprio 0
	s_cmpk_gt_u32 s20, 0xff
	v_readlane_b32 s25, v253, 41
	v_readlane_b32 s27, v253, 43
	v_readlane_b32 s29, v253, 45
	v_readlane_b32 s31, v253, 47
	v_readlane_b32 s35, v253, 49
	s_cbranch_scc1 .LBB0_254
	s_barrier
